# 6a gate sigmoid and 6c SwiGLU epilogues use v_rcp_f32 + one Newton step (f32) instead of the IEEE division sequence; attention S->max hazard nop widened
# speedup vs baseline: 1.0977x; 1.0059x over previous
; #define MFMA32(a, b, c) __builtin_amdgcn_mfma_f32_32x32x16_bf16((a), (b), (c), 0, 0, 0)
; DI void attn_item(const Ctx& c, int item) {
;     ...
; #pragma unroll
;     for (int ks = 0; ks < 12; ++ks)
; #pragma unroll
;       for (int kg = 0; kg < 2; ++kg) {
;         const bf16x8 a = *(const bf16x8*)(ks_ + (kg * 32 + r32) * 200 + ks * 16 + 8 * hh);
;         s[kg] = MFMA32(a, bq[ks], s[kg]);
;       }
;     float mx = s[0][0];
; #pragma unroll
;     for (int kg = 0; kg < 2; ++kg)
; #pragma unroll
;       for (int i = 0; i < 16; ++i) mx = fmaxf(mx, s[kg][i]);
;     mx = fmaxf(mx, __shfl_xor(mx, 32));
;     const float mn = fmaxf(m_, mx * sc);
;     const float alpha = __builtin_amdgcn_exp2f(m_ - mn);
;     m_ = mn;
;     float ps = 0.f;
; #pragma unroll
;     for (int kg = 0; kg < 2; ++kg)
; #pragma unroll
;       for (int i = 0; i < 16; ++i) { s[kg][i] = __builtin_amdgcn_exp2f(s[kg][i] * sc - mn); ps += s[kg][i]; }
;     l_ = l_ * alpha + ps;
;     if (__builtin_amdgcn_ballot_w64(alpha != 1.0f) != 0ull) {
; #pragma unroll
;       for (int dt = 0; dt < 4; ++dt)
; #pragma unroll
;         for (int i = 0; i < 16; ++i) oacc[dt][i] *= alpha;
;     }
.Lattn_noload:
	s_waitcnt lgkmcnt(3)
	v_mfma_f32_32x32x16_bf16 v[82:97], v[230:233], v[114:117], v[82:97]
	ds_read_b128 v[230:233], v211 offset:192
	s_waitcnt lgkmcnt(3)
	v_mfma_f32_32x32x16_bf16 v[66:81], v[234:237], v[114:117], v[66:81]
	ds_read_b128 v[234:237], v211 offset:12992
	s_waitcnt lgkmcnt(3)
	v_mfma_f32_32x32x16_bf16 v[82:97], v[238:241], v[118:121], v[82:97]
	ds_read_b128 v[238:241], v211 offset:224
	s_waitcnt lgkmcnt(3)
	v_mfma_f32_32x32x16_bf16 v[66:81], v[242:245], v[118:121], v[66:81]
	ds_read_b128 v[242:245], v211 offset:13024
	s_waitcnt lgkmcnt(3)
	v_mfma_f32_32x32x16_bf16 v[82:97], v[230:233], v[122:125], v[82:97]
	ds_read_b128 v[230:233], v211 offset:256
	s_waitcnt lgkmcnt(3)
	v_mfma_f32_32x32x16_bf16 v[66:81], v[234:237], v[122:125], v[66:81]
	ds_read_b128 v[234:237], v211 offset:13056
	s_waitcnt lgkmcnt(3)
	v_mfma_f32_32x32x16_bf16 v[82:97], v[238:241], v[126:129], v[82:97]
	ds_read_b128 v[238:241], v211 offset:288
	s_waitcnt lgkmcnt(3)
	v_mfma_f32_32x32x16_bf16 v[66:81], v[242:245], v[126:129], v[66:81]
	ds_read_b128 v[242:245], v211 offset:13088
	s_waitcnt lgkmcnt(3)
	v_mfma_f32_32x32x16_bf16 v[82:97], v[230:233], v[130:133], v[82:97]
	ds_read_b128 v[230:233], v211 offset:320
	s_waitcnt lgkmcnt(3)
	v_mfma_f32_32x32x16_bf16 v[66:81], v[234:237], v[130:133], v[66:81]
	ds_read_b128 v[234:237], v211 offset:13120
	s_waitcnt lgkmcnt(3)
	v_mfma_f32_32x32x16_bf16 v[82:97], v[238:241], v[134:137], v[82:97]
	ds_read_b128 v[238:241], v211 offset:352
	s_waitcnt lgkmcnt(3)
	v_mfma_f32_32x32x16_bf16 v[66:81], v[242:245], v[134:137], v[66:81]
	ds_read_b128 v[242:245], v211 offset:13152
	s_waitcnt lgkmcnt(3)
	v_mfma_f32_32x32x16_bf16 v[82:97], v[230:233], v[138:141], v[82:97]
	s_waitcnt lgkmcnt(2)
	v_mfma_f32_32x32x16_bf16 v[66:81], v[234:237], v[138:141], v[66:81]
	s_waitcnt lgkmcnt(1)
	v_mfma_f32_32x32x16_bf16 v[82:97], v[238:241], v[142:145], v[82:97]
	s_waitcnt lgkmcnt(0)
	v_mfma_f32_32x32x16_bf16 v[66:81], v[242:245], v[142:145], v[66:81]
	s_mulk_i32 s0, 0x4800
	v_add_u32_e32 v224, s0, v209
	ds_read_b128 v[230:233], v224 offset:51200
	ds_read_b128 v[234:237], v224 offset:55808
	ds_read_b128 v[238:241], v224 offset:60416
	ds_read_b128 v[242:245], v224 offset:65024
	ds_read_b128 v[246:249], v224 offset:51232
	s_nop 2
	v_max_f32_e32 v211, v83, v83
	v_max_f32_e32 v212, v82, v82
	v_max_f32_e32 v211, v212, v211
	v_max3_f32 v211, v211, v84, v85
	v_max3_f32 v211, v211, v86, v87
	v_max3_f32 v211, v211, v88, v89
	v_max3_f32 v211, v211, v90, v91
	v_max3_f32 v211, v211, v92, v93
	v_max3_f32 v211, v211, v94, v95
	v_max3_f32 v211, v211, v96, v97
	v_max3_f32 v211, v211, v66, v67
	v_max3_f32 v211, v211, v68, v69
	v_max3_f32 v211, v211, v70, v71
	v_max3_f32 v211, v211, v72, v73
	v_max3_f32 v211, v211, v74, v75
	v_max3_f32 v211, v211, v76, v77
	v_max3_f32 v211, v211, v78, v79
	v_max3_f32 v211, v211, v80, v81
	ds_bpermute_b32 v212, v207, v211
	s_waitcnt lgkmcnt(0)
	v_max_f32_e32 v212, v212, v212
	v_max_f32_e32 v211, v211, v212
	v_mul_f32_e32 v211, 0x3dd53b94, v211
	v_max_f32_e32 v212, v0, v0
	v_max_f32_e32 v211, v212, v211
	v_sub_f32_e32 v0, v0, v211
	v_exp_f32_e32 v0, v0
	s_nop 0
	v_cmp_neq_f32_e32 vcc, 1.0, v0
	s_cbranch_vccz .LBB0_549
	v_pk_mul_f32 v[64:65], v[64:65], v[0:1] op_sel_hi:[1,0]
	v_pk_mul_f32 v[62:63], v[62:63], v[0:1] op_sel_hi:[1,0]
	v_pk_mul_f32 v[60:61], v[60:61], v[0:1] op_sel_hi:[1,0]
	v_pk_mul_f32 v[58:59], v[58:59], v[0:1] op_sel_hi:[1,0]
	v_pk_mul_f32 v[56:57], v[56:57], v[0:1] op_sel_hi:[1,0]
	v_pk_mul_f32 v[54:55], v[54:55], v[0:1] op_sel_hi:[1,0]
	v_pk_mul_f32 v[52:53], v[52:53], v[0:1] op_sel_hi:[1,0]
	v_pk_mul_f32 v[50:51], v[50:51], v[0:1] op_sel_hi:[1,0]
	v_pk_mul_f32 v[48:49], v[48:49], v[0:1] op_sel_hi:[1,0]
	v_pk_mul_f32 v[46:47], v[46:47], v[0:1] op_sel_hi:[1,0]
	v_pk_mul_f32 v[44:45], v[44:45], v[0:1] op_sel_hi:[1,0]
	v_pk_mul_f32 v[42:43], v[42:43], v[0:1] op_sel_hi:[1,0]
	v_pk_mul_f32 v[40:41], v[40:41], v[0:1] op_sel_hi:[1,0]
	v_pk_mul_f32 v[38:39], v[38:39], v[0:1] op_sel_hi:[1,0]
	v_pk_mul_f32 v[36:37], v[36:37], v[0:1] op_sel_hi:[1,0]
	v_pk_mul_f32 v[34:35], v[34:35], v[0:1] op_sel_hi:[1,0]
	v_pk_mul_f32 v[32:33], v[32:33], v[0:1] op_sel_hi:[1,0]
	v_pk_mul_f32 v[30:31], v[30:31], v[0:1] op_sel_hi:[1,0]
	v_pk_mul_f32 v[28:29], v[28:29], v[0:1] op_sel_hi:[1,0]
	v_pk_mul_f32 v[26:27], v[26:27], v[0:1] op_sel_hi:[1,0]
	v_pk_mul_f32 v[24:25], v[24:25], v[0:1] op_sel_hi:[1,0]
	v_pk_mul_f32 v[22:23], v[22:23], v[0:1] op_sel_hi:[1,0]
	v_pk_mul_f32 v[20:21], v[20:21], v[0:1] op_sel_hi:[1,0]
	v_pk_mul_f32 v[18:19], v[18:19], v[0:1] op_sel_hi:[1,0]
	v_pk_mul_f32 v[16:17], v[16:17], v[0:1] op_sel_hi:[1,0]
	v_pk_mul_f32 v[14:15], v[14:15], v[0:1] op_sel_hi:[1,0]
	v_pk_mul_f32 v[12:13], v[12:13], v[0:1] op_sel_hi:[1,0]
	v_pk_mul_f32 v[10:11], v[10:11], v[0:1] op_sel_hi:[1,0]
	v_pk_mul_f32 v[8:9], v[8:9], v[0:1] op_sel_hi:[1,0]
	v_pk_mul_f32 v[6:7], v[6:7], v[0:1] op_sel_hi:[1,0]
	v_pk_mul_f32 v[4:5], v[4:5], v[0:1] op_sel_hi:[1,0]
	v_pk_mul_f32 v[2:3], v[2:3], v[0:1] op_sel_hi:[1,0]

; #define MFMA16(a, b, c) __builtin_amdgcn_mfma_f32_16x16x32_bf16((a), (b), (c), 0, 0, 0)
; #define RAW_BARRIER() do { asm volatile("s_waitcnt lgkmcnt(0)" ::: "memory"); __builtin_amdgcn_s_barrier(); } while (0)
; template <int WM, int MI, int NJ, typename AT>
; DI void gemm2(f32x4 (&acc)[MI][NJ], const AT* A, int lda, const bf16* Bt, int ldb, int K, bf16* lds) {
;     ...
;   for (int kt = 0; kt < nk; ++kt) {
;     if (kt + 1 < nk) wait_vm<NL>(); else wait_vm<0>();
;     RAW_BARRIER();
;     if (kt + 2 < nk) { const int st2 = (st + 2 >= 3) ? st - 1 : st + 2; G3_ISSUE(kt + 2, st2) }
;     const bf16* sp = lds + st * G3_STAGE;
; #pragma unroll
;     for (int kk = 0; kk < 2; ++kk) {
;       bf16x8 a[MI], b[NJ];
; #pragma unroll
;       for (int i = 0; i < MI; ++i) a[i] = *(const bf16x8*)(sp + (aoff[i] ^ (kk << 5)));
; #pragma unroll
;       for (int j = 0; j < NJ; ++j) b[j] = *(const bf16x8*)(sp + (boff[j] ^ (kk << 5)));
; #pragma unroll
;       for (int i = 0; i < MI; ++i)
; #pragma unroll
;         for (int j = 0; j < NJ; ++j) acc[i][j] = MFMA16(a[i], b[j], acc[i][j]);
;     }
;     st = (st == 2) ? 0 : st + 1;
;   }
.LBB0_806:
	s_cmp_gt_i32 s13, 0
	s_cselect_b32 s14, -1, 2
	s_add_i32 s14, s14, s13
	s_mul_i32 s14, s14, 0xc000
	v_add_u32_e32 v134, s14, v131
	v_lshl_add_u64 v[114:115], v[112:113], 0, s[44:45]
	v_readfirstlane_b32 s14, v134
	s_waitcnt vmcnt(4)
	v_lshl_add_u64 v[116:117], v[114:115], 0, s[68:69]
	s_mov_b32 m0, s14
	v_add_u32_e32 v120, 0x2000, v134
	s_waitcnt lgkmcnt(0)
	s_barrier
	global_load_lds_dwordx4 v[116:117], off
	v_lshl_add_u64 v[116:117], v[110:111], 0, s[44:45]
	v_readfirstlane_b32 s14, v120
	v_lshl_add_u64 v[118:119], v[116:117], 0, s[68:69]
	s_mov_b32 m0, s14
	v_add_u32_e32 v132, 0x4000, v134
	global_load_lds_dwordx4 v[118:119], off
	v_lshl_add_u64 v[118:119], v[108:109], 0, s[44:45]
	v_readfirstlane_b32 s14, v132
	v_add_u32_e32 v134, 0x6000, v134
	v_lshl_add_u64 v[120:121], v[118:119], 0, s[72:73]
	s_mov_b32 m0, s14
	v_readfirstlane_b32 s14, v134
	global_load_lds_dwordx4 v[120:121], off
	v_lshl_add_u64 v[120:121], v[106:107], 0, s[44:45]
	s_mov_b32 m0, s14
	s_mul_i32 s14, s13, 0xc000
	v_lshl_add_u64 v[132:133], v[120:121], 0, s[72:73]
	s_addk_i32 s14, 0x50
	v_lshlrev_b32_e32 v165, 1, v125
	v_lshlrev_b32_e32 v202, 1, v124
	global_load_lds_dwordx4 v[132:133], off
	v_add_u32_e32 v136, s14, v165
	v_add_u32_e32 v140, s14, v202
	v_lshlrev_b32_e32 v203, 1, v0
	ds_read_b128 v[132:135], v136
	ds_read_b128 v[136:139], v136 offset:2048
	ds_read_b128 v[166:169], v140 offset:16384
	v_add_u32_e32 v140, s14, v203
	ds_read_b128 v[170:173], v140 offset:2048
	ds_read_b128 v[174:177], v140 offset:4096
	ds_read_b128 v[178:181], v140 offset:6144
	s_waitcnt lgkmcnt(0)
	v_mfma_f32_16x16x32_bf16 v[50:53], v[132:135], v[166:169], v[50:53]
	v_lshl_add_u64 v[114:115], v[114:115], 0, s[74:75]
	v_mfma_f32_16x16x32_bf16 v[46:49], v[132:135], v[170:173], v[46:49]
	v_mfma_f32_16x16x32_bf16 v[42:45], v[132:135], v[174:177], v[42:45]
	v_mfma_f32_16x16x32_bf16 v[38:41], v[132:135], v[178:181], v[38:41]
	v_lshlrev_b32_e32 v132, 1, v130
	v_lshlrev_b32_e32 v133, 1, v129
	v_lshlrev_b32_e32 v135, 1, v128
	v_mfma_f32_16x16x32_bf16 v[34:37], v[136:139], v[166:169], v[34:37]
	v_add_u32_e32 v134, s14, v135
	v_mfma_f32_16x16x32_bf16 v[166:169], v[136:139], v[174:177], v[26:29]
	s_nop 2
	v_add_u32_e32 v26, s14, v132
	v_mfma_f32_16x16x32_bf16 v[30:33], v[136:139], v[170:173], v[30:33]
	v_mfma_f32_16x16x32_bf16 v[138:141], v[136:139], v[178:181], v[22:25]
	s_nop 2
	ds_read_b128 v[22:25], v26
	ds_read_b128 v[170:173], v26 offset:2048
	v_add_u32_e32 v26, s14, v133
	ds_read_b128 v[26:29], v26
	ds_read_b128 v[174:177], v134
	v_lshlrev_b32_e32 v134, 1, v127
	v_add_u32_e32 v136, s14, v134
	ds_read_b128 v[178:181], v136
	v_lshlrev_b32_e32 v136, 1, v126
	v_add_u32_e32 v137, s14, v136
	s_add_i32 s14, s13, 1
	s_cmp_lg_u32 s13, 2
	s_cselect_b32 s13, s14, 0
	s_cmp_gt_i32 s13, 0
	s_cselect_b32 s14, -1, 2
	s_add_i32 s14, s14, s13
	s_mul_i32 s14, s14, 0xc000
	ds_read_b128 v[182:185], v137
	v_add_u32_e32 v137, s14, v131
	s_waitcnt vmcnt(4)
	s_waitcnt lgkmcnt(0)
	s_barrier
	v_readfirstlane_b32 s14, v137
	s_mov_b32 m0, s14
	s_waitcnt lgkmcnt(0)
	v_mfma_f32_16x16x32_bf16 v[50:53], v[22:25], v[26:29], v[50:53]
	global_load_lds_dwordx4 v[114:115], off
	v_lshl_add_u64 v[114:115], v[116:117], 0, s[74:75]
	v_add_u32_e32 v116, 0x2000, v137
	v_mfma_f32_16x16x32_bf16 v[46:49], v[22:25], v[174:177], v[46:49]
	v_readfirstlane_b32 s14, v116
	v_add_u32_e32 v116, 0x4000, v137
	s_mov_b32 m0, s14
	v_readfirstlane_b32 s14, v116
	v_add_u32_e32 v116, 0x6000, v137
	global_load_lds_dwordx4 v[114:115], off
	v_lshl_add_u64 v[114:115], v[118:119], 0, s[76:77]
	s_mov_b32 m0, s14
	v_readfirstlane_b32 s14, v116
	global_load_lds_dwordx4 v[114:115], off
	v_lshl_add_u64 v[114:115], v[120:121], 0, s[76:77]
	s_mov_b32 m0, s14
	s_mul_i32 s14, s13, 0xc000
	global_load_lds_dwordx4 v[114:115], off
	s_add_i32 s46, s14, 0x50
	v_add_u32_e32 v118, s46, v165
	v_add_u32_e32 v137, s46, v202
	v_mfma_f32_16x16x32_bf16 v[42:45], v[22:25], v[178:181], v[42:45]
	ds_read_b128 v[114:117], v118
	ds_read_b128 v[118:121], v118 offset:2048
	v_add_u32_e32 v136, s46, v136
	s_add_i32 s14, s13, 1
	v_mfma_f32_16x16x32_bf16 v[38:41], v[22:25], v[182:185], v[38:41]
	s_cmp_lg_u32 s13, 2
	s_cselect_b32 s13, s14, 0
	s_add_u32 s44, s44, 0x100
	v_mfma_f32_16x16x32_bf16 v[22:25], v[170:173], v[26:29], v[34:37]
	s_addc_u32 s45, s45, 0
	s_cmpk_eq_i32 s44, 0x300
	v_mfma_f32_16x16x32_bf16 v[34:37], v[170:173], v[182:185], v[138:141]
	s_nop 2
	ds_read_b128 v[138:141], v137 offset:16384
	v_add_u32_e32 v137, s46, v203
	v_mfma_f32_16x16x32_bf16 v[26:29], v[170:173], v[174:177], v[30:33]
	v_mfma_f32_16x16x32_bf16 v[30:33], v[170:173], v[178:181], v[166:169]
	s_nop 2
	ds_read_b128 v[166:169], v137 offset:2048
	ds_read_b128 v[170:173], v137 offset:4096
	ds_read_b128 v[174:177], v137 offset:6144
	s_waitcnt lgkmcnt(0)
	v_mfma_f32_16x16x32_bf16 v[50:53], v[114:117], v[138:141], v[50:53]
	v_mfma_f32_16x16x32_bf16 v[46:49], v[114:117], v[166:169], v[46:49]
	v_mfma_f32_16x16x32_bf16 v[42:45], v[114:117], v[170:173], v[42:45]
	v_mfma_f32_16x16x32_bf16 v[38:41], v[114:117], v[174:177], v[38:41]
	v_mfma_f32_16x16x32_bf16 v[22:25], v[118:121], v[138:141], v[22:25]
	v_mfma_f32_16x16x32_bf16 v[26:29], v[118:121], v[166:169], v[26:29]
	v_mfma_f32_16x16x32_bf16 v[114:117], v[118:121], v[170:173], v[30:33]
	v_mfma_f32_16x16x32_bf16 v[118:121], v[118:121], v[174:177], v[34:37]
	s_nop 2
	v_add_u32_e32 v34, s46, v132
	ds_read_b128 v[30:33], v34
	ds_read_b128 v[138:141], v34 offset:2048
	v_add_u32_e32 v34, s46, v133
	v_add_u32_e32 v132, s46, v135
	ds_read_b128 v[34:37], v34
	ds_read_b128 v[166:169], v132
	v_add_u32_e32 v132, s46, v134
	ds_read_b128 v[132:135], v132
	ds_read_b128 v[170:173], v136
	s_waitcnt lgkmcnt(0)
	v_mfma_f32_16x16x32_bf16 v[50:53], v[30:33], v[34:37], v[50:53]
	v_mfma_f32_16x16x32_bf16 v[46:49], v[30:33], v[166:169], v[46:49]
	v_mfma_f32_16x16x32_bf16 v[42:45], v[30:33], v[132:135], v[42:45]
	v_mfma_f32_16x16x32_bf16 v[38:41], v[30:33], v[170:173], v[38:41]
	v_mfma_f32_16x16x32_bf16 v[34:37], v[138:141], v[34:37], v[22:25]
	v_mfma_f32_16x16x32_bf16 v[30:33], v[138:141], v[166:169], v[26:29]
	v_mfma_f32_16x16x32_bf16 v[26:29], v[138:141], v[132:135], v[114:117]
	v_mfma_f32_16x16x32_bf16 v[22:25], v[138:141], v[170:173], v[118:121]
	s_cbranch_scc0 .LBB0_806
; DI float sigmoidf_(float x) { return 1.f / (1.f + __expf(-x)); }
; DI void phase_tail(const Ctx& c) {
;     ...
; #pragma unroll
;           for (int i = 0; i < 2; ++i)
; #pragma unroll
;             for (int j = 0; j < 4; ++j) {
;               const int row0 = wm2 * 32 + i * 16 + (lane >> 4) * 4;
;               gp[i][j][0] = pack2(sigmoidf_(ag[i][j][0] * rstd[row0]), sigmoidf_(ag[i][j][1] * rstd[row0 + 1]));
;               gp[i][j][1] = pack2(sigmoidf_(ag[i][j][2] * rstd[row0 + 2]), sigmoidf_(ag[i][j][3] * rstd[row0 + 3]));
;             }
	v_mul_f32_e32 v70, v70, v58
	v_mul_f32_e32 v71, v71, v59
	v_mul_f32_e32 v72, v72, v60
	v_mul_f32_e32 v73, v73, v61
	v_mul_f32_e32 v66, v66, v58
	v_mul_f32_e32 v67, v67, v59
	v_mul_f32_e32 v68, v68, v60
	v_mul_f32_e32 v69, v69, v61
	v_mul_f32_e32 v70, 0xbfb8aa3b, v70
	v_mul_f32_e32 v71, 0xbfb8aa3b, v71
	v_mul_f32_e32 v72, 0xbfb8aa3b, v72
	v_mul_f32_e32 v73, 0xbfb8aa3b, v73
	v_mul_f32_e32 v66, 0xbfb8aa3b, v66
	v_mul_f32_e32 v67, 0xbfb8aa3b, v67
	v_mul_f32_e32 v68, 0xbfb8aa3b, v68
	v_mul_f32_e32 v69, 0xbfb8aa3b, v69
	v_exp_f32_e32 v70, v70
	v_exp_f32_e32 v71, v71
	v_exp_f32_e32 v72, v72
	v_exp_f32_e32 v73, v73
	v_exp_f32_e32 v66, v66
	v_exp_f32_e32 v67, v67
	v_exp_f32_e32 v68, v68
	v_exp_f32_e32 v69, v69
	v_add_f32_e32 v70, 1.0, v70
	v_add_f32_e32 v71, 1.0, v71
	v_add_f32_e32 v72, 1.0, v72
	v_add_f32_e32 v73, 1.0, v73
	v_add_f32_e32 v66, 1.0, v66
	v_add_f32_e32 v67, 1.0, v67
	v_add_f32_e32 v68, 1.0, v68
	v_add_f32_e32 v69, 1.0, v69
	v_min_f32_e32 v70, 0x7f7fffff, v70
	v_min_f32_e32 v71, 0x7f7fffff, v71
	v_min_f32_e32 v72, 0x7f7fffff, v72
	v_min_f32_e32 v73, 0x7f7fffff, v73
	v_min_f32_e32 v66, 0x7f7fffff, v66
	v_min_f32_e32 v67, 0x7f7fffff, v67
	v_min_f32_e32 v68, 0x7f7fffff, v68
	v_min_f32_e32 v69, 0x7f7fffff, v69
	v_rcp_f32_e32 v230, v70
	v_rcp_f32_e32 v231, v71
	v_rcp_f32_e32 v232, v72
	v_rcp_f32_e32 v233, v73
	v_rcp_f32_e32 v234, v66
	v_rcp_f32_e32 v235, v67
	v_rcp_f32_e32 v236, v68
	v_rcp_f32_e32 v237, v69
	v_fma_f32 v240, -v70, v230, 1.0
	v_fma_f32 v241, -v71, v231, 1.0
	v_fma_f32 v242, -v72, v232, 1.0
	v_fma_f32 v243, -v73, v233, 1.0
	v_fma_f32 v244, -v66, v234, 1.0
	v_fma_f32 v245, -v67, v235, 1.0
	v_fma_f32 v246, -v68, v236, 1.0
	v_fma_f32 v247, -v69, v237, 1.0
	v_fma_f32 v70, v240, v230, v230
	v_fma_f32 v71, v241, v231, v231
	v_fma_f32 v72, v242, v232, v232
	v_fma_f32 v73, v243, v233, v233
	v_fma_f32 v66, v244, v234, v234
	v_fma_f32 v67, v245, v235, v235
	v_fma_f32 v68, v246, v236, v236
	v_fma_f32 v69, v247, v237, v237
	v_mul_f32_e32 v62, v62, v58
	v_mul_f32_e32 v63, v63, v59
	v_mul_f32_e32 v64, v64, v60
	v_mul_f32_e32 v65, v65, v61
	v_mul_f32_e32 v54, v54, v58
	v_mul_f32_e32 v55, v55, v59
	v_mul_f32_e32 v56, v56, v60
	v_mul_f32_e32 v57, v57, v61
	v_mul_f32_e32 v62, 0xbfb8aa3b, v62
	v_mul_f32_e32 v63, 0xbfb8aa3b, v63
	v_mul_f32_e32 v64, 0xbfb8aa3b, v64
	v_mul_f32_e32 v65, 0xbfb8aa3b, v65
	v_mul_f32_e32 v54, 0xbfb8aa3b, v54
	v_mul_f32_e32 v55, 0xbfb8aa3b, v55
	v_mul_f32_e32 v56, 0xbfb8aa3b, v56
	v_mul_f32_e32 v57, 0xbfb8aa3b, v57
	v_exp_f32_e32 v62, v62
	v_exp_f32_e32 v63, v63
	v_exp_f32_e32 v64, v64
	v_exp_f32_e32 v65, v65
	v_exp_f32_e32 v54, v54
	v_exp_f32_e32 v55, v55
	v_exp_f32_e32 v56, v56
	v_exp_f32_e32 v57, v57
	v_add_f32_e32 v62, 1.0, v62
	v_add_f32_e32 v63, 1.0, v63
	v_add_f32_e32 v64, 1.0, v64
	v_add_f32_e32 v65, 1.0, v65
	v_add_f32_e32 v54, 1.0, v54
	v_add_f32_e32 v55, 1.0, v55
	v_add_f32_e32 v56, 1.0, v56
	v_add_f32_e32 v57, 1.0, v57
	v_min_f32_e32 v62, 0x7f7fffff, v62
	v_min_f32_e32 v63, 0x7f7fffff, v63
	v_min_f32_e32 v64, 0x7f7fffff, v64
	v_min_f32_e32 v65, 0x7f7fffff, v65
	v_min_f32_e32 v54, 0x7f7fffff, v54
	v_min_f32_e32 v55, 0x7f7fffff, v55
	v_min_f32_e32 v56, 0x7f7fffff, v56
	v_min_f32_e32 v57, 0x7f7fffff, v57
	v_rcp_f32_e32 v230, v62
	v_rcp_f32_e32 v231, v63
	v_rcp_f32_e32 v232, v64
	v_rcp_f32_e32 v233, v65
	v_rcp_f32_e32 v234, v54
	v_rcp_f32_e32 v235, v55
	v_rcp_f32_e32 v236, v56
	v_rcp_f32_e32 v237, v57
	v_fma_f32 v240, -v62, v230, 1.0
	v_fma_f32 v241, -v63, v231, 1.0
	v_fma_f32 v242, -v64, v232, 1.0
	v_fma_f32 v243, -v65, v233, 1.0
	v_fma_f32 v244, -v54, v234, 1.0
	v_fma_f32 v245, -v55, v235, 1.0
	v_fma_f32 v246, -v56, v236, 1.0
	v_fma_f32 v247, -v57, v237, 1.0
	v_fma_f32 v62, v240, v230, v230
	v_fma_f32 v63, v241, v231, v231
	v_fma_f32 v64, v242, v232, v232
	v_fma_f32 v65, v243, v233, v233
	v_fma_f32 v54, v244, v234, v234
	v_fma_f32 v55, v245, v235, v235
	v_fma_f32 v56, v246, v236, v236
	v_fma_f32 v57, v247, v237, v237
	v_mul_f32_e32 v18, v18, v6
	v_mul_f32_e32 v19, v19, v7
	v_mul_f32_e32 v20, v20, v8
	v_mul_f32_e32 v21, v21, v9
	v_mul_f32_e32 v14, v14, v6
	v_mul_f32_e32 v15, v15, v7
	v_mul_f32_e32 v16, v16, v8
	v_mul_f32_e32 v17, v17, v9
	v_mul_f32_e32 v18, 0xbfb8aa3b, v18
	v_mul_f32_e32 v19, 0xbfb8aa3b, v19
	v_mul_f32_e32 v20, 0xbfb8aa3b, v20
	v_mul_f32_e32 v21, 0xbfb8aa3b, v21
	v_mul_f32_e32 v14, 0xbfb8aa3b, v14
	v_mul_f32_e32 v15, 0xbfb8aa3b, v15
	v_mul_f32_e32 v16, 0xbfb8aa3b, v16
	v_mul_f32_e32 v17, 0xbfb8aa3b, v17
	v_exp_f32_e32 v18, v18
	v_exp_f32_e32 v19, v19
	v_exp_f32_e32 v20, v20
	v_exp_f32_e32 v21, v21
	v_exp_f32_e32 v14, v14
	v_exp_f32_e32 v15, v15
	v_exp_f32_e32 v16, v16
	v_exp_f32_e32 v17, v17
	v_add_f32_e32 v18, 1.0, v18
	v_add_f32_e32 v19, 1.0, v19
	v_add_f32_e32 v20, 1.0, v20
	v_add_f32_e32 v21, 1.0, v21
	v_add_f32_e32 v14, 1.0, v14
	v_add_f32_e32 v15, 1.0, v15
	v_add_f32_e32 v16, 1.0, v16
	v_add_f32_e32 v17, 1.0, v17
	v_min_f32_e32 v18, 0x7f7fffff, v18
	v_min_f32_e32 v19, 0x7f7fffff, v19
	v_min_f32_e32 v20, 0x7f7fffff, v20
	v_min_f32_e32 v21, 0x7f7fffff, v21
	v_min_f32_e32 v14, 0x7f7fffff, v14
	v_min_f32_e32 v15, 0x7f7fffff, v15
	v_min_f32_e32 v16, 0x7f7fffff, v16
	v_min_f32_e32 v17, 0x7f7fffff, v17
	v_rcp_f32_e32 v230, v18
	v_rcp_f32_e32 v231, v19
	v_rcp_f32_e32 v232, v20
	v_rcp_f32_e32 v233, v21
	v_rcp_f32_e32 v234, v14
	v_rcp_f32_e32 v235, v15
	v_rcp_f32_e32 v236, v16
	v_rcp_f32_e32 v237, v17
	v_fma_f32 v240, -v18, v230, 1.0
	v_fma_f32 v241, -v19, v231, 1.0
	v_fma_f32 v242, -v20, v232, 1.0
	v_fma_f32 v243, -v21, v233, 1.0
	v_fma_f32 v244, -v14, v234, 1.0
	v_fma_f32 v245, -v15, v235, 1.0
	v_fma_f32 v246, -v16, v236, 1.0
	v_fma_f32 v247, -v17, v237, 1.0
	v_fma_f32 v18, v240, v230, v230
; #define MFMA16(a, b, c) __builtin_amdgcn_mfma_f32_16x16x32_bf16((a), (b), (c), 0, 0, 0)
; DI float sigmoidf_(float x) { return 1.f / (1.f + __expf(-x)); }
; template <int WM, int MI, int NJ, typename AT>
; DI void gemm2(f32x4 (&acc)[MI][NJ], const AT* A, int lda, const bf16* Bt, int ldb, int K, bf16* lds) {
;     ...
;     for (int kk = 0; kk < 2; ++kk) {
;       bf16x8 a[MI], b[NJ];
; #pragma unroll
;       for (int i = 0; i < MI; ++i) a[i] = *(const bf16x8*)(sp + (aoff[i] ^ (kk << 5)));
; #pragma unroll
;       for (int j = 0; j < NJ; ++j) b[j] = *(const bf16x8*)(sp + (boff[j] ^ (kk << 5)));
; #pragma unroll
;       for (int i = 0; i < MI; ++i)
; #pragma unroll
;         for (int j = 0; j < NJ; ++j) acc[i][j] = MFMA16(a[i], b[j], acc[i][j]);
;     }
; DI void phase_tail(const Ctx& c) {
;     ...
; #pragma unroll
;           for (int i = 0; i < 2; ++i)
; #pragma unroll
;             for (int j = 0; j < 4; ++j) {
;               const int row0 = wm2 * 32 + i * 16 + (lane >> 4) * 4;
;               gp[i][j][0] = pack2(sigmoidf_(ag[i][j][0] * rstd[row0]), sigmoidf_(ag[i][j][1] * rstd[row0 + 1]));
;               gp[i][j][1] = pack2(sigmoidf_(ag[i][j][2] * rstd[row0 + 2]), sigmoidf_(ag[i][j][3] * rstd[row0 + 3]));
;             }
	v_fma_f32 v19, v241, v231, v231
	v_fma_f32 v20, v242, v232, v232
	v_fma_f32 v21, v243, v233, v233
	v_fma_f32 v14, v244, v234, v234
	v_fma_f32 v15, v245, v235, v235
	v_fma_f32 v16, v246, v236, v236
	v_fma_f32 v17, v247, v237, v237
	v_mul_f32_e32 v10, v10, v6
	v_mul_f32_e32 v11, v11, v7
	v_mul_f32_e32 v12, v12, v8
	v_mul_f32_e32 v13, v13, v9
	v_mul_f32_e32 v2, v2, v6
	v_mul_f32_e32 v3, v3, v7
	v_mul_f32_e32 v4, v4, v8
	v_mul_f32_e32 v5, v5, v9
	v_mul_f32_e32 v10, 0xbfb8aa3b, v10
	v_mul_f32_e32 v11, 0xbfb8aa3b, v11
	v_mul_f32_e32 v12, 0xbfb8aa3b, v12
	v_mul_f32_e32 v13, 0xbfb8aa3b, v13
	v_mul_f32_e32 v2, 0xbfb8aa3b, v2
	v_mul_f32_e32 v3, 0xbfb8aa3b, v3
	v_mul_f32_e32 v4, 0xbfb8aa3b, v4
	v_mul_f32_e32 v5, 0xbfb8aa3b, v5
	v_exp_f32_e32 v10, v10
	v_exp_f32_e32 v11, v11
	v_exp_f32_e32 v12, v12
	v_exp_f32_e32 v13, v13
	v_exp_f32_e32 v2, v2
	v_exp_f32_e32 v3, v3
	v_exp_f32_e32 v4, v4
	v_exp_f32_e32 v5, v5
	v_add_f32_e32 v10, 1.0, v10
	v_add_f32_e32 v11, 1.0, v11
	v_add_f32_e32 v12, 1.0, v12
	v_add_f32_e32 v13, 1.0, v13
	v_add_f32_e32 v2, 1.0, v2
	v_add_f32_e32 v3, 1.0, v3
	v_add_f32_e32 v4, 1.0, v4
	v_add_f32_e32 v5, 1.0, v5
	v_min_f32_e32 v10, 0x7f7fffff, v10
	v_min_f32_e32 v11, 0x7f7fffff, v11
	v_min_f32_e32 v12, 0x7f7fffff, v12
	v_min_f32_e32 v13, 0x7f7fffff, v13
	v_min_f32_e32 v2, 0x7f7fffff, v2
	v_min_f32_e32 v3, 0x7f7fffff, v3
	v_min_f32_e32 v4, 0x7f7fffff, v4
	v_min_f32_e32 v5, 0x7f7fffff, v5
	v_rcp_f32_e32 v230, v10
	v_rcp_f32_e32 v231, v11
	v_rcp_f32_e32 v232, v12
	v_rcp_f32_e32 v233, v13
	v_rcp_f32_e32 v234, v2
	v_rcp_f32_e32 v235, v3
	v_rcp_f32_e32 v236, v4
	v_rcp_f32_e32 v237, v5
	v_fma_f32 v240, -v10, v230, 1.0
	v_fma_f32 v241, -v11, v231, 1.0
	v_fma_f32 v242, -v12, v232, 1.0
	v_fma_f32 v243, -v13, v233, 1.0
	v_fma_f32 v244, -v2, v234, 1.0
	v_fma_f32 v245, -v3, v235, 1.0
	v_fma_f32 v246, -v4, v236, 1.0
	v_fma_f32 v247, -v5, v237, 1.0
	v_fma_f32 v10, v240, v230, v230
	v_fma_f32 v11, v241, v231, v231
	v_fma_f32 v12, v242, v232, v232
	v_fma_f32 v13, v243, v233, v233
	v_fma_f32 v2, v244, v234, v234
	v_fma_f32 v3, v245, v235, v235
	v_fma_f32 v4, v246, v236, v236
	v_fma_f32 v5, v247, v237, v237
	s_waitcnt vmcnt(4)
	v_lshl_add_u32 v125, v125, 1, v190
	v_lshl_add_u32 v106, v124, 1, v190
	v_lshl_add_u32 v0, v0, 1, v190
	s_waitcnt lgkmcnt(0)
	s_barrier
	ds_read_b128 v[6:9], v125
	ds_read_b128 v[58:61], v125 offset:2048
	ds_read_b128 v[106:109], v106 offset:16384
	ds_read_b128 v[110:113], v0 offset:2048
	ds_read_b128 v[114:117], v0 offset:4096
	ds_read_b128 v[118:121], v0 offset:6144
	v_lshl_add_u32 v124, v130, 1, v190
	v_lshl_add_u32 v129, v129, 1, v190
	s_waitcnt lgkmcnt(0)
	v_mfma_f32_16x16x32_bf16 v[50:53], v[6:9], v[106:109], v[50:53]
	v_lshl_add_u32 v128, v128, 1, v190
	v_lshl_add_u32 v127, v127, 1, v190
	v_lshl_add_u32 v126, v126, 1, v190
	v_mfma_f32_16x16x32_bf16 v[46:49], v[6:9], v[110:113], v[46:49]
	v_cvt_pk_bf16_f32 v71, v71, s0
	v_cvt_pk_bf16_f32 v70, v70, s0
	v_lshlrev_b32_e32 v71, 16, v71
	v_mfma_f32_16x16x32_bf16 v[42:45], v[6:9], v[114:117], v[42:45]
	v_cvt_pk_bf16_f32 v73, v73, s0
	v_cvt_pk_bf16_f32 v72, v72, s0
	v_lshlrev_b32_e32 v73, 16, v73
	v_mfma_f32_16x16x32_bf16 v[6:9], v[6:9], v[118:121], v[38:41]
	v_cvt_pk_bf16_f32 v67, v67, s0
	v_cvt_pk_bf16_f32 v66, v66, s0
	v_lshlrev_b32_e32 v67, 16, v67
	v_mfma_f32_16x16x32_bf16 v[34:37], v[58:61], v[106:109], v[34:37]
	v_cvt_pk_bf16_f32 v69, v69, s0
	v_cvt_pk_bf16_f32 v68, v68, s0
	v_lshlrev_b32_e32 v69, 16, v69
	v_mfma_f32_16x16x32_bf16 v[30:33], v[58:61], v[110:113], v[30:33]
	v_cvt_pk_bf16_f32 v63, v63, s0
	v_cvt_pk_bf16_f32 v62, v62, s0
	v_lshlrev_b32_e32 v63, 16, v63
	v_mfma_f32_16x16x32_bf16 v[26:29], v[58:61], v[114:117], v[26:29]
	v_cvt_pk_bf16_f32 v65, v65, s0
	v_cvt_pk_bf16_f32 v64, v64, s0
	v_lshlrev_b32_e32 v65, 16, v65
	v_mfma_f32_16x16x32_bf16 v[22:25], v[58:61], v[118:121], v[22:25]
	ds_read_b128 v[38:41], v124
	ds_read_b128 v[58:61], v124 offset:2048
	ds_read_b128 v[106:109], v129
	ds_read_b128 v[110:113], v128
	ds_read_b128 v[114:117], v127
	ds_read_b128 v[118:121], v126
	s_waitcnt lgkmcnt(0)
	v_mfma_f32_16x16x32_bf16 v[50:53], v[38:41], v[106:109], v[50:53]
	s_waitcnt vmcnt(0)
	s_waitcnt lgkmcnt(0)
	s_barrier
	v_mfma_f32_16x16x32_bf16 v[46:49], v[38:41], v[110:113], v[46:49]
	v_cvt_pk_bf16_f32 v55, v55, s0
	v_cvt_pk_bf16_f32 v54, v54, s0
	v_lshlrev_b32_e32 v55, 16, v55
	v_mfma_f32_16x16x32_bf16 v[42:45], v[38:41], v[114:117], v[42:45]
	v_cvt_pk_bf16_f32 v57, v57, s0
	v_cvt_pk_bf16_f32 v56, v56, s0
	v_lshlrev_b32_e32 v57, 16, v57
	v_mfma_f32_16x16x32_bf16 v[6:9], v[38:41], v[118:121], v[6:9]
	v_cvt_pk_bf16_f32 v19, v19, s0
	v_cvt_pk_bf16_f32 v18, v18, s0
	v_lshlrev_b32_e32 v19, 16, v19
	v_mfma_f32_16x16x32_bf16 v[34:37], v[58:61], v[106:109], v[34:37]
	v_cvt_pk_bf16_f32 v21, v21, s0
	s_add_i32 s82, s82, 1
	v_cvt_pk_bf16_f32 v20, v20, s0
	v_mfma_f32_16x16x32_bf16 v[30:33], v[58:61], v[110:113], v[30:33]
	v_lshlrev_b32_e32 v21, 16, v21
	v_cvt_pk_bf16_f32 v15, v15, s0
	s_add_u32 s42, s42, 0x200000
	v_mfma_f32_16x16x32_bf16 v[26:29], v[58:61], v[114:117], v[26:29]
	v_cvt_pk_bf16_f32 v14, v14, s0
	v_lshlrev_b32_e32 v15, 16, v15
	v_cvt_pk_bf16_f32 v17, v17, s0
	v_mfma_f32_16x16x32_bf16 v[22:25], v[58:61], v[118:121], v[22:25]
	ds_read_b128 v[38:41], v125 offset:49152
	ds_read_b128 v[58:61], v125 offset:51200
	ds_read_b128 v[106:109], v0 offset:49152
	ds_read_b128 v[110:113], v0 offset:51200
	ds_read_b128 v[114:117], v0 offset:53248
	ds_read_b128 v[118:121], v0 offset:55296
	s_addc_u32 s43, s43, 0
	v_cvt_pk_bf16_f32 v16, v16, s0
	s_waitcnt lgkmcnt(0)
; DI float lo16(unsigned u) { return __uint_as_float(u << 16); }
; DI float hi16(unsigned u) { return __uint_as_float(u & 0xffff0000u); }
; template <int BN_OUT> DI void ct_put(bf16* lds, int row, int col, float v) { lds[row * (BN_OUT + 8) + col] = f2bf(v); }
; DI void phase_tail(const Ctx& c) {
;     ...
; #pragma unroll
;         for (int i = 0; i < 2; ++i)
; #pragma unroll
;           for (int j = 0; j < 4; ++j) {
;             am[i][j][0] += lo16(gp[i][j][0]) * ab[i][j][0]; am[i][j][1] += hi16(gp[i][j][0]) * ab[i][j][1];
;             am[i][j][2] += lo16(gp[i][j][1]) * ab[i][j][2]; am[i][j][3] += hi16(gp[i][j][1]) * ab[i][j][3];
;           }
;       }
;       __syncthreads();
;       ACC2_FOREACH(4, 2, 4, ct_put<128>(lds, row, col, am[i][j][r]);)
;       ct_flush<128, 128>(lds, MERGED + (size_t)m0 * 1024 + nt * 128, 1024);
	v_mfma_f32_16x16x32_bf16 v[50:53], v[38:41], v[106:109], v[50:53]
	v_lshlrev_b32_e32 v17, 16, v17
	v_cvt_pk_bf16_f32 v11, v11, s0
	v_cvt_pk_bf16_f32 v3, v3, s0
	v_mfma_f32_16x16x32_bf16 v[46:49], v[38:41], v[110:113], v[46:49]
	s_add_u32 s40, s40, 0x100000
	v_cvt_pk_bf16_f32 v10, v10, s0
	v_lshlrev_b32_e32 v11, 16, v11
	v_mfma_f32_16x16x32_bf16 v[42:45], v[38:41], v[114:117], v[42:45]
	v_cvt_pk_bf16_f32 v13, v13, s0
	v_cvt_pk_bf16_f32 v2, v2, s0
	v_lshlrev_b32_e32 v3, 16, v3
	v_mfma_f32_16x16x32_bf16 v[6:9], v[38:41], v[118:121], v[6:9]
	v_cvt_pk_bf16_f32 v5, v5, s0
	s_addc_u32 s41, s41, 0
	v_cvt_pk_bf16_f32 v12, v12, s0
	v_mfma_f32_16x16x32_bf16 v[34:37], v[58:61], v[106:109], v[34:37]
	v_lshlrev_b32_e32 v13, 16, v13
	v_cvt_pk_bf16_f32 v4, v4, s0
	v_lshlrev_b32_e32 v5, 16, v5
	v_mfma_f32_16x16x32_bf16 v[30:33], v[58:61], v[110:113], v[30:33]
	v_lshlrev_b32_e32 v2, 16, v2
	v_and_b32_e32 v3, 0xffff0000, v3
	s_add_u32 s38, s38, 0x2000000
	v_mfma_f32_16x16x32_bf16 v[26:29], v[58:61], v[114:117], v[26:29]
	s_addc_u32 s39, s39, 0
	s_cmp_eq_u32 s82, 3
	v_mfma_f32_16x16x32_bf16 v[22:25], v[58:61], v[118:121], v[22:25]
	ds_read_b128 v[38:41], v124 offset:49152
	ds_read_b128 v[58:61], v124 offset:51200
	ds_read_b128 v[106:109], v129 offset:49152
	ds_read_b128 v[110:113], v128 offset:49152
	ds_read_b128 v[114:117], v127 offset:49152
	ds_read_b128 v[118:121], v126 offset:49152
	s_waitcnt lgkmcnt(0)
	v_mfma_f32_16x16x32_bf16 v[50:53], v[38:41], v[106:109], v[50:53]
	v_mfma_f32_16x16x32_bf16 v[46:49], v[38:41], v[110:113], v[46:49]
	v_mfma_f32_16x16x32_bf16 v[42:45], v[38:41], v[114:117], v[42:45]
	v_mfma_f32_16x16x32_bf16 v[6:9], v[38:41], v[118:121], v[6:9]
	v_lshlrev_b32_e32 v38, 16, v70
	v_and_b32_e32 v39, 0xffff0000, v71
	s_nop 2
	v_pk_fma_f32 v[104:105], v[50:51], v[38:39], v[104:105]
	v_lshlrev_b32_e32 v38, 16, v72
	v_and_b32_e32 v39, 0xffff0000, v73
	v_pk_fma_f32 v[102:103], v[52:53], v[38:39], v[102:103]
	v_lshlrev_b32_e32 v38, 16, v66
	v_and_b32_e32 v39, 0xffff0000, v67
	v_pk_fma_f32 v[100:101], v[46:47], v[38:39], v[100:101]
	v_lshlrev_b32_e32 v38, 16, v68
	v_and_b32_e32 v39, 0xffff0000, v69
	v_pk_fma_f32 v[98:99], v[48:49], v[38:39], v[98:99]
	v_lshlrev_b32_e32 v38, 16, v62
	v_and_b32_e32 v39, 0xffff0000, v63
	v_mfma_f32_16x16x32_bf16 v[34:37], v[58:61], v[106:109], v[34:37]
	v_fma_f32 v96, v42, v38, v96
	v_fma_f32 v97, v43, v39, v97
	v_lshlrev_b32_e32 v38, 16, v64
	v_and_b32_e32 v39, 0xffff0000, v65
	v_pk_fma_f32 v[94:95], v[44:45], v[38:39], v[94:95]
	v_lshlrev_b32_e32 v38, 16, v54
	v_and_b32_e32 v39, 0xffff0000, v55
	v_mfma_f32_16x16x32_bf16 v[30:33], v[58:61], v[110:113], v[30:33]
	v_fma_f32 v92, v6, v38, v92
	v_fma_f32 v93, v7, v39, v93
	v_lshlrev_b32_e32 v6, 16, v56
	v_and_b32_e32 v7, 0xffff0000, v57
	v_pk_fma_f32 v[90:91], v[8:9], v[6:7], v[90:91]
	v_lshlrev_b32_e32 v6, 16, v18
	v_and_b32_e32 v7, 0xffff0000, v19
	v_mfma_f32_16x16x32_bf16 v[26:29], v[58:61], v[114:117], v[26:29]
	v_fma_f32 v88, v34, v6, v88
	v_fma_f32 v89, v35, v7, v89
	v_lshlrev_b32_e32 v6, 16, v20
	v_and_b32_e32 v7, 0xffff0000, v21
	v_mfma_f32_16x16x32_bf16 v[22:25], v[58:61], v[118:121], v[22:25]
	v_fma_f32 v86, v36, v6, v86
	v_fma_f32 v87, v37, v7, v87
	v_lshlrev_b32_e32 v6, 16, v14
	v_and_b32_e32 v7, 0xffff0000, v15
	v_pk_fma_f32 v[84:85], v[30:31], v[6:7], v[84:85]
	v_lshlrev_b32_e32 v6, 16, v16
	v_and_b32_e32 v7, 0xffff0000, v17
	v_pk_fma_f32 v[82:83], v[32:33], v[6:7], v[82:83]
	v_lshlrev_b32_e32 v6, 16, v10
	v_and_b32_e32 v7, 0xffff0000, v11
	v_pk_fma_f32 v[80:81], v[26:27], v[6:7], v[80:81]
	v_lshlrev_b32_e32 v6, 16, v12
	v_and_b32_e32 v7, 0xffff0000, v13
	v_pk_fma_f32 v[76:77], v[22:23], v[2:3], v[76:77]
	v_lshlrev_b32_e32 v2, 16, v4
	v_and_b32_e32 v3, 0xffff0000, v5
	v_pk_fma_f32 v[78:79], v[28:29], v[6:7], v[78:79]
	v_pk_fma_f32 v[74:75], v[24:25], v[2:3], v[74:75]
	s_cbranch_scc0 .LBB0_803
	v_mov_b32_e32 v0, v186
	v_mov_b32_e32 v2, v186
	s_waitcnt vmcnt(0)
	s_barrier
	s_mov_b32 s13, 0xfffffe0
	v_ashrrev_i32_e32 v3, 6, v2
	v_lshrrev_b32_e32 v2, 31, v2
	v_add_u32_e32 v2, v3, v2
	v_and_b32_e32 v4, 0x1fffffe, v2
	v_sub_u32_e32 v3, v3, v4
	v_lshrrev_b32_e32 v4, 2, v0
	v_lshlrev_b32_e32 v2, 4, v2
	v_and_b32_e32 v4, 12, v4
	v_and_b32_e32 v0, 15, v0
	v_and_or_b32 v2, v2, s13, v4
	s_movk_i32 s13, 0x110
	v_lshlrev_b32_e32 v0, 1, v0
	v_mul_lo_u32 v2, v2, s13
	v_lshl_or_b32 v0, v3, 7, v0
	s_movk_i32 s13, 0x50
	v_add3_u32 v3, s13, v2, v0
	v_add3_u32 v0, s13, v0, v2
	v_cvt_pk_bf16_f32 v2, v101, s0
	ds_write_b16 v3, v2 offset:304
	v_cvt_pk_bf16_f32 v2, v98, s0
	ds_write_b16 v3, v2 offset:576
	v_cvt_pk_bf16_f32 v2, v99, s0
	v_cvt_pk_bf16_f32 v4, v104, s0
	ds_write_b16 v3, v2 offset:848
	v_cvt_pk_bf16_f32 v2, v96, s0
	ds_write_b16 v3, v4
	v_cvt_pk_bf16_f32 v4, v105, s0
	ds_write_b16 v0, v2 offset:64
	v_cvt_pk_bf16_f32 v2, v97, s0
	ds_write_b16 v3, v4 offset:272
	v_cvt_pk_bf16_f32 v4, v102, s0
	ds_write_b16 v3, v2 offset:336
	v_cvt_pk_bf16_f32 v2, v94, s0
	ds_write_b16 v3, v4 offset:544
	v_cvt_pk_bf16_f32 v4, v103, s0
	ds_write_b16 v3, v2 offset:608
	v_cvt_pk_bf16_f32 v2, v95, s0
	ds_write_b16 v3, v4 offset:816
	v_cvt_pk_bf16_f32 v4, v100, s0
	ds_write_b16 v3, v2 offset:880
	v_cvt_pk_bf16_f32 v2, v92, s0
	ds_write_b16 v0, v4 offset:32
	ds_write_b16 v0, v2 offset:96
	v_cvt_pk_bf16_f32 v0, v93, s0
	ds_write_b16 v3, v0 offset:368
	v_cvt_pk_bf16_f32 v0, v90, s0
	ds_write_b16 v3, v0 offset:640
	v_cvt_pk_bf16_f32 v0, v91, s0
	ds_write_b16 v3, v0 offset:912
	v_cvt_pk_bf16_f32 v0, v88, s0
	ds_write_b16 v3, v0 offset:4352
	v_cvt_pk_bf16_f32 v0, v89, s0
	ds_write_b16 v3, v0 offset:4624
	v_cvt_pk_bf16_f32 v0, v86, s0
	ds_write_b16 v3, v0 offset:4896
	v_cvt_pk_bf16_f32 v0, v87, s0
	ds_write_b16 v3, v0 offset:5168
	v_cvt_pk_bf16_f32 v0, v84, s0
	ds_write_b16 v3, v0 offset:4384
	v_cvt_pk_bf16_f32 v0, v85, s0
	ds_write_b16 v3, v0 offset:4656
	v_cvt_pk_bf16_f32 v0, v82, s0
	ds_write_b16 v3, v0 offset:4928
	v_cvt_pk_bf16_f32 v0, v83, s0
	ds_write_b16 v3, v0 offset:5200
	v_cvt_pk_bf16_f32 v0, v80, s0
	ds_write_b16 v3, v0 offset:4416
	v_cvt_pk_bf16_f32 v0, v81, s0
	ds_write_b16 v3, v0 offset:4688
	v_cvt_pk_bf16_f32 v0, v78, s0
	ds_write_b16 v3, v0 offset:4960
	v_cvt_pk_bf16_f32 v0, v79, s0
	ds_write_b16 v3, v0 offset:5232
	v_cvt_pk_bf16_f32 v0, v76, s0
	ds_write_b16 v3, v0 offset:4448
	v_cvt_pk_bf16_f32 v0, v77, s0
	ds_write_b16 v3, v0 offset:4720
	v_cvt_pk_bf16_f32 v0, v74, s0
	ds_write_b16 v3, v0 offset:4992
	v_cvt_pk_bf16_f32 v0, v75, s0
	ds_write_b16 v3, v0 offset:5264
	v_mov_b32_e32 v0, v186
	s_movk_i32 s13, 0x800
	s_waitcnt lgkmcnt(0)
	s_barrier
	s_nop 0
	v_cmp_gt_i32_e32 vcc, s13, v0
	s_and_saveexec_b64 s[38:39], vcc
	s_movk_i32 s13, 0x5ff
	s_cbranch_execz .LBB0_801
	s_lshl_b32 s12, s12, 1
	s_add_u32 s40, s20, s12
	s_addc_u32 s41, s21, 0
	v_lshl_add_u32 v2, v0, 4, v190
	v_lshlrev_b32_e32 v3, 3, v0
	s_mov_b64 s[42:43], 0

; #define MFMA16(a, b, c) __builtin_amdgcn_mfma_f32_16x16x32_bf16((a), (b), (c), 0, 0, 0)
; #define RAW_BARRIER() do { asm volatile("s_waitcnt lgkmcnt(0)" ::: "memory"); __builtin_amdgcn_s_barrier(); } while (0)
; template <int WM, int MI, int NJ, typename AT>
; DI void gemm2(f32x4 (&acc)[MI][NJ], const AT* A, int lda, const bf16* Bt, int ldb, int K, bf16* lds) {
;     ...
;   for (int kt = 0; kt < nk; ++kt) {
;     if (kt + 1 < nk) wait_vm<NL>(); else wait_vm<0>();
;     RAW_BARRIER();
;     if (kt + 2 < nk) { const int st2 = (st + 2 >= 3) ? st - 1 : st + 2; G3_ISSUE(kt + 2, st2) }
;     const bf16* sp = lds + st * G3_STAGE;
; #pragma unroll
;     for (int kk = 0; kk < 2; ++kk) {
;       bf16x8 a[MI], b[NJ];
; #pragma unroll
;       for (int i = 0; i < MI; ++i) a[i] = *(const bf16x8*)(sp + (aoff[i] ^ (kk << 5)));
; #pragma unroll
;       for (int j = 0; j < NJ; ++j) b[j] = *(const bf16x8*)(sp + (boff[j] ^ (kk << 5)));
; #pragma unroll
;       for (int i = 0; i < MI; ++i)
; #pragma unroll
;         for (int j = 0; j < NJ; ++j) acc[i][j] = MFMA16(a[i], b[j], acc[i][j]);
;     }
;     st = (st == 2) ? 0 : st + 1;
;   }
.LBB0_855:
	s_cmp_gt_i32 s11, 0
	s_cselect_b32 s12, -1, 2
	s_add_i32 s12, s12, s11
	s_mul_i32 s12, s12, 0xc000
	v_add_u32_e32 v88, s12, v85
	v_add_u32_e32 v89, 0x2000, v88
	v_readfirstlane_b32 s12, v88
	s_waitcnt vmcnt(6)
	v_lshl_add_u64 v[86:87], v[76:77], 0, s[28:29]
	s_mov_b32 m0, s12
	v_readfirstlane_b32 s12, v89
	v_add_u32_e32 v89, 0x4000, v88
	s_waitcnt lgkmcnt(0)
	s_barrier
	global_load_lds_dwordx4 v[86:87], off
	v_lshl_add_u64 v[86:87], v[74:75], 0, s[28:29]
	s_mov_b32 m0, s12
	v_readfirstlane_b32 s12, v89
	v_add_u32_e32 v89, 0x6000, v88
	global_load_lds_dwordx4 v[86:87], off
	v_lshl_add_u64 v[86:87], v[72:73], 0, s[28:29]
	s_mov_b32 m0, s12
	v_readfirstlane_b32 s12, v89
	v_add_u32_e32 v89, 0x8000, v88
	global_load_lds_dwordx4 v[86:87], off
	v_lshl_add_u64 v[86:87], v[70:71], 0, s[28:29]
	s_mov_b32 m0, s12
	v_readfirstlane_b32 s12, v89
	v_add_u32_e32 v88, 0xa000, v88
	global_load_lds_dwordx4 v[86:87], off
	v_lshl_add_u64 v[86:87], v[68:69], 0, s[28:29]
	s_mov_b32 m0, s12
	v_readfirstlane_b32 s12, v88
	global_load_lds_dwordx4 v[86:87], off
	v_lshl_add_u64 v[86:87], v[66:67], 0, s[28:29]
	s_mov_b32 m0, s12
	s_mul_i32 s12, s11, 0xc000
	global_load_lds_dwordx4 v[86:87], off
	s_addk_i32 s12, 0x50
	v_lshl_add_u32 v98, v84, 1, s12
	v_lshl_add_u32 v102, v83, 1, s12
	v_lshl_add_u32 v114, v82, 1, s12
	ds_read_b128 v[86:89], v98
	ds_read_b128 v[90:93], v98 offset:2048
	ds_read_b128 v[94:97], v98 offset:4096
	ds_read_b128 v[98:101], v98 offset:6144
	ds_read_b128 v[102:105], v102 offset:16384
	ds_read_b128 v[106:109], v114 offset:2048
	ds_read_b128 v[110:113], v114 offset:4096
	ds_read_b128 v[114:117], v114 offset:6144
	s_waitcnt lgkmcnt(0)
	v_mfma_f32_16x16x32_bf16 v[62:65], v[86:89], v[102:105], v[62:65]
	v_mfma_f32_16x16x32_bf16 v[58:61], v[86:89], v[106:109], v[58:61]
	v_mfma_f32_16x16x32_bf16 v[54:57], v[86:89], v[110:113], v[54:57]
	v_mfma_f32_16x16x32_bf16 v[50:53], v[86:89], v[114:117], v[50:53]
	v_mfma_f32_16x16x32_bf16 v[46:49], v[90:93], v[102:105], v[46:49]
	v_mfma_f32_16x16x32_bf16 v[42:45], v[90:93], v[106:109], v[42:45]
	v_mfma_f32_16x16x32_bf16 v[38:41], v[90:93], v[110:113], v[38:41]
	v_mfma_f32_16x16x32_bf16 v[34:37], v[90:93], v[114:117], v[34:37]
	v_mfma_f32_16x16x32_bf16 v[30:33], v[94:97], v[102:105], v[30:33]
	v_mfma_f32_16x16x32_bf16 v[26:29], v[94:97], v[106:109], v[26:29]
	v_mfma_f32_16x16x32_bf16 v[22:25], v[94:97], v[110:113], v[22:25]
	v_mfma_f32_16x16x32_bf16 v[18:21], v[94:97], v[114:117], v[18:21]
	v_mfma_f32_16x16x32_bf16 v[14:17], v[98:101], v[102:105], v[14:17]
	v_lshl_add_u32 v102, v80, 1, s12
	v_mfma_f32_16x16x32_bf16 v[10:13], v[98:101], v[106:109], v[10:13]
	v_lshl_add_u32 v106, v79, 1, s12
	v_mfma_f32_16x16x32_bf16 v[6:9], v[98:101], v[110:113], v[6:9]
	v_lshl_add_u32 v110, v78, 1, s12
	v_mfma_f32_16x16x32_bf16 v[2:5], v[98:101], v[114:117], v[2:5]
	v_lshl_add_u32 v98, v81, 1, s12
	v_lshl_add_u32 v114, v0, 1, s12
	ds_read_b128 v[86:89], v98
	ds_read_b128 v[90:93], v98 offset:2048
	ds_read_b128 v[94:97], v98 offset:4096
	ds_read_b128 v[98:101], v98 offset:6144
	ds_read_b128 v[102:105], v102
	ds_read_b128 v[106:109], v106
	ds_read_b128 v[110:113], v110
	ds_read_b128 v[114:117], v114
	s_add_i32 s12, s11, 1
	s_waitcnt lgkmcnt(0)
	v_mfma_f32_16x16x32_bf16 v[62:65], v[86:89], v[102:105], v[62:65]
	s_cmp_lg_u32 s11, 2
	s_cselect_b32 s11, s12, 0
	s_add_u32 s28, s28, 0x80
	v_mfma_f32_16x16x32_bf16 v[58:61], v[86:89], v[106:109], v[58:61]
	s_addc_u32 s29, s29, 0
	s_cmpk_lg_i32 s28, 0x700
	v_mfma_f32_16x16x32_bf16 v[54:57], v[86:89], v[110:113], v[54:57]
	v_mfma_f32_16x16x32_bf16 v[50:53], v[86:89], v[114:117], v[50:53]
	v_mfma_f32_16x16x32_bf16 v[46:49], v[90:93], v[102:105], v[46:49]
	v_mfma_f32_16x16x32_bf16 v[42:45], v[90:93], v[106:109], v[42:45]
	v_mfma_f32_16x16x32_bf16 v[38:41], v[90:93], v[110:113], v[38:41]
	v_mfma_f32_16x16x32_bf16 v[34:37], v[90:93], v[114:117], v[34:37]
	v_mfma_f32_16x16x32_bf16 v[30:33], v[94:97], v[102:105], v[30:33]
	v_mfma_f32_16x16x32_bf16 v[26:29], v[94:97], v[106:109], v[26:29]
	v_mfma_f32_16x16x32_bf16 v[22:25], v[94:97], v[110:113], v[22:25]
	v_mfma_f32_16x16x32_bf16 v[18:21], v[94:97], v[114:117], v[18:21]
	v_mfma_f32_16x16x32_bf16 v[14:17], v[98:101], v[102:105], v[14:17]
	v_mfma_f32_16x16x32_bf16 v[10:13], v[98:101], v[106:109], v[10:13]
	v_mfma_f32_16x16x32_bf16 v[6:9], v[98:101], v[110:113], v[6:9]
	v_mfma_f32_16x16x32_bf16 v[2:5], v[98:101], v[114:117], v[2:5]
	s_cbranch_scc1 .LBB0_855
	s_mul_i32 s11, s11, 0xc000
	s_addk_i32 s11, 0x50
	v_lshlrev_b32_e32 v104, 1, v84
	v_lshlrev_b32_e32 v105, 1, v83
	v_lshlrev_b32_e32 v106, 1, v82
	s_waitcnt vmcnt(6)
	v_add_u32_e32 v84, s11, v104
	v_add_u32_e32 v83, s11, v105
	v_add_u32_e32 v82, s11, v106
	s_waitcnt lgkmcnt(0)
	s_barrier
; #define MFMA16(a, b, c) __builtin_amdgcn_mfma_f32_16x16x32_bf16((a), (b), (c), 0, 0, 0)
; template <int WM, int MI, int NJ, typename AT>
; DI void gemm2(f32x4 (&acc)[MI][NJ], const AT* A, int lda, const bf16* Bt, int ldb, int K, bf16* lds) {
;     ...
;     const bf16* sp = lds + st * G3_STAGE;
; #pragma unroll
;     for (int kk = 0; kk < 2; ++kk) {
;       bf16x8 a[MI], b[NJ];
; #pragma unroll
;       for (int i = 0; i < MI; ++i) a[i] = *(const bf16x8*)(sp + (aoff[i] ^ (kk << 5)));
; #pragma unroll
;       for (int j = 0; j < NJ; ++j) b[j] = *(const bf16x8*)(sp + (boff[j] ^ (kk << 5)));
; #pragma unroll
;       for (int i = 0; i < MI; ++i)
; #pragma unroll
;         for (int j = 0; j < NJ; ++j) acc[i][j] = MFMA16(a[i], b[j], acc[i][j]);
;     }
	ds_read_b128 v[66:69], v84
	ds_read_b128 v[70:73], v84 offset:2048
	ds_read_b128 v[74:77], v84 offset:4096
	ds_read_b128 v[84:87], v84 offset:6144
	ds_read_b128 v[88:91], v83 offset:16384
	ds_read_b128 v[92:95], v82 offset:2048
	ds_read_b128 v[96:99], v82 offset:4096
	ds_read_b128 v[100:103], v82 offset:6144
	s_waitcnt lgkmcnt(0)
	v_mfma_f32_16x16x32_bf16 v[50:53], v[66:69], v[100:103], v[50:53]
	v_lshlrev_b32_e32 v107, 1, v79
	v_lshlrev_b32_e32 v108, 1, v78
	v_lshlrev_b32_e32 v0, 1, v0
	v_mfma_f32_16x16x32_bf16 v[34:37], v[70:73], v[100:103], v[34:37]
	v_add_u32_e32 v79, s11, v107
	v_add_u32_e32 v78, s11, v108
	v_mfma_f32_16x16x32_bf16 v[18:21], v[74:77], v[100:103], v[18:21]
	v_mfma_f32_16x16x32_bf16 v[2:5], v[84:87], v[100:103], v[2:5]
	v_lshlrev_b32_e32 v102, 1, v81
	v_lshlrev_b32_e32 v103, 1, v80
	v_add_u32_e32 v81, s11, v102
	v_mfma_f32_16x16x32_bf16 v[58:61], v[66:69], v[92:95], v[58:61]
	v_add_u32_e32 v80, s11, v103
	v_mfma_f32_16x16x32_bf16 v[42:45], v[70:73], v[92:95], v[42:45]
	v_mfma_f32_16x16x32_bf16 v[26:29], v[74:77], v[92:95], v[26:29]
	v_mfma_f32_16x16x32_bf16 v[10:13], v[84:87], v[92:95], v[10:13]
	v_add_u32_e32 v94, s11, v0
	v_add_u32_e32 v0, 0x50, v0
	s_movk_i32 s11, 0x800
	v_mfma_f32_16x16x32_bf16 v[62:65], v[66:69], v[88:91], v[62:65]
	v_mfma_f32_16x16x32_bf16 v[54:57], v[66:69], v[96:99], v[54:57]
	v_mfma_f32_16x16x32_bf16 v[46:49], v[70:73], v[88:91], v[46:49]
	v_mfma_f32_16x16x32_bf16 v[38:41], v[70:73], v[96:99], v[38:41]
	v_mfma_f32_16x16x32_bf16 v[30:33], v[74:77], v[88:91], v[30:33]
	v_mfma_f32_16x16x32_bf16 v[22:25], v[74:77], v[96:99], v[22:25]
	v_mfma_f32_16x16x32_bf16 v[14:17], v[84:87], v[88:91], v[14:17]
	v_mfma_f32_16x16x32_bf16 v[6:9], v[84:87], v[96:99], v[6:9]
	ds_read_b128 v[66:69], v81
	ds_read_b128 v[70:73], v81 offset:2048
	ds_read_b128 v[74:77], v81 offset:4096
	ds_read_b128 v[82:85], v81 offset:6144
	ds_read_b128 v[86:89], v80
	ds_read_b128 v[90:93], v79
	ds_read_b128 v[78:81], v78
	ds_read_b128 v[94:97], v94
	s_waitcnt lgkmcnt(0)
	v_mfma_f32_16x16x32_bf16 v[54:57], v[66:69], v[78:81], v[54:57]
	s_waitcnt vmcnt(0)
	s_waitcnt lgkmcnt(0)
	s_barrier
	v_mfma_f32_16x16x32_bf16 v[50:53], v[66:69], v[94:97], v[50:53]
	v_mfma_f32_16x16x32_bf16 v[38:41], v[70:73], v[78:81], v[38:41]
	v_mfma_f32_16x16x32_bf16 v[34:37], v[70:73], v[94:97], v[34:37]
	v_mfma_f32_16x16x32_bf16 v[22:25], v[74:77], v[78:81], v[22:25]
	v_mfma_f32_16x16x32_bf16 v[18:21], v[74:77], v[94:97], v[18:21]
	v_mfma_f32_16x16x32_bf16 v[14:17], v[82:85], v[86:89], v[14:17]
	v_mfma_f32_16x16x32_bf16 v[10:13], v[82:85], v[90:93], v[10:13]
	v_mfma_f32_16x16x32_bf16 v[6:9], v[82:85], v[78:81], v[6:9]
	v_add_u32_e32 v78, 0x50, v104
	v_mfma_f32_16x16x32_bf16 v[2:5], v[82:85], v[94:97], v[2:5]
	v_add_u32_e32 v82, 0x50, v105
	v_add_u32_e32 v94, 0x50, v106
	v_mfma_f32_16x16x32_bf16 v[62:65], v[66:69], v[86:89], v[62:65]
	v_mfma_f32_16x16x32_bf16 v[58:61], v[66:69], v[90:93], v[58:61]
	v_mfma_f32_16x16x32_bf16 v[46:49], v[70:73], v[86:89], v[46:49]
	v_mfma_f32_16x16x32_bf16 v[42:45], v[70:73], v[90:93], v[42:45]
	v_mfma_f32_16x16x32_bf16 v[30:33], v[74:77], v[86:89], v[30:33]
	v_mfma_f32_16x16x32_bf16 v[26:29], v[74:77], v[90:93], v[26:29]
	ds_read_b128 v[66:69], v78
	ds_read_b128 v[70:73], v78 offset:2048
	ds_read_b128 v[74:77], v78 offset:4096
	ds_read_b128 v[78:81], v78 offset:6144
	ds_read_b128 v[82:85], v82 offset:16384
	ds_read_b128 v[86:89], v94 offset:2048
	ds_read_b128 v[90:93], v94 offset:4096
	ds_read_b128 v[94:97], v94 offset:6144
	s_waitcnt lgkmcnt(0)
	v_mfma_f32_16x16x32_bf16 v[30:33], v[74:77], v[82:85], v[30:33]
	v_mfma_f32_16x16x32_bf16 v[98:101], v[74:77], v[86:89], v[26:29]
	v_mfma_f32_16x16x32_bf16 v[22:25], v[74:77], v[90:93], v[22:25]
	v_mfma_f32_16x16x32_bf16 v[74:77], v[74:77], v[94:97], v[18:21]
	s_nop 2
	v_add_u32_e32 v18, 0x50, v102
	v_mfma_f32_16x16x32_bf16 v[62:65], v[66:69], v[82:85], v[62:65]
	v_mfma_f32_16x16x32_bf16 v[58:61], v[66:69], v[86:89], v[58:61]
	v_mfma_f32_16x16x32_bf16 v[54:57], v[66:69], v[90:93], v[54:57]
	v_mfma_f32_16x16x32_bf16 v[50:53], v[66:69], v[94:97], v[50:53]
	v_mfma_f32_16x16x32_bf16 v[46:49], v[70:73], v[82:85], v[46:49]
	v_mfma_f32_16x16x32_bf16 v[66:69], v[70:73], v[86:89], v[42:45]
	v_mfma_f32_16x16x32_bf16 v[38:41], v[70:73], v[90:93], v[38:41]
	v_mfma_f32_16x16x32_bf16 v[14:17], v[78:81], v[82:85], v[14:17]
	v_mfma_f32_16x16x32_bf16 v[82:85], v[78:81], v[86:89], v[10:13]
	v_mfma_f32_16x16x32_bf16 v[6:9], v[78:81], v[90:93], v[6:9]
	v_mfma_f32_16x16x32_bf16 v[78:81], v[78:81], v[94:97], v[2:5]
	s_nop 2
	ds_read_b128 v[2:5], v18
	ds_read_b128 v[10:13], v18 offset:2048
	ds_read_b128 v[86:89], v18 offset:4096
	ds_read_b128 v[90:93], v18 offset:6144
	v_add_u32_e32 v18, 0x50, v103
	ds_read_b128 v[110:113], v0
	v_mfma_f32_16x16x32_bf16 v[70:73], v[70:73], v[94:97], v[34:37]
	ds_read_b128 v[94:97], v18
	v_add_u32_e32 v18, 0x50, v107
	ds_read_b128 v[102:105], v18
	v_add_u32_e32 v18, 0x50, v108
	ds_read_b128 v[106:109], v18
	s_waitcnt lgkmcnt(0)
	v_mfma_f32_16x16x32_bf16 v[42:45], v[10:13], v[94:97], v[46:49]
	s_waitcnt vmcnt(0)
	s_barrier
; DI float siluf_(float x) { return x / (1.f + __expf(-x)); }
; template <int BN_OUT> DI void ct_put(bf16* lds, int row, int col, float v) { lds[row * (BN_OUT + 8) + col] = f2bf(v); }
; DI void phase_tail(const Ctx& c) {
;     ...
;       __syncthreads();
; #pragma unroll
;       for (int i = 0; i < 4; ++i)
; #pragma unroll
;         for (int r = 0; r < 4; ++r) {
;           const int row = wm * 64 + i * 16 + (lane >> 4) * 4 + r;
;           const float rs = rstd2[row];
; #pragma unroll
;           for (int pp = 0; pp < 2; ++pp) {
;             const float g = acc[i][2 * pp][r] * rs, u = acc[i][2 * pp + 1][r] * rs;
;             ct_put<128>(lds, row, (wn * 2 + pp) * 16 + (lane & 15), siluf_(g) * u);
;           }
;         }
	v_mfma_f32_16x16x32_bf16 v[46:49], v[10:13], v[102:105], v[66:69]
	s_nop 2
	ds_read_b128 v[66:69], v143
	v_mfma_f32_16x16x32_bf16 v[62:65], v[2:5], v[94:97], v[62:65]
	v_mfma_f32_16x16x32_bf16 v[34:37], v[10:13], v[106:109], v[38:41]
	v_mfma_f32_16x16x32_bf16 v[38:41], v[10:13], v[110:113], v[70:73]
	s_waitcnt lgkmcnt(0)
	s_nop 4
	v_mul_f32_e32 v0, v62, v66
	v_mul_f32_e32 v62, 0xbfb8aa3b, v0
	v_exp_f32_e32 v62, v62
	v_mfma_f32_16x16x32_bf16 v[58:61], v[2:5], v[102:105], v[58:61]
	v_add_f32_e32 v62, 1.0, v62
	v_div_scale_f32 v70, s[12:13], v62, v62, v0
	v_rcp_f32_e32 v71, v70
	v_mfma_f32_16x16x32_bf16 v[18:21], v[86:89], v[106:109], v[22:25]
	s_nop 3
	v_mul_f32_e32 v58, v58, v66
	v_fma_f32 v72, -v70, v71, 1.0
	v_fmac_f32_e32 v71, v72, v71
	v_div_scale_f32 v72, vcc, v0, v62, v0
	v_mul_f32_e32 v73, v72, v71
	v_mfma_f32_16x16x32_bf16 v[22:25], v[86:89], v[110:113], v[74:77]
	s_nop 2
	v_fma_f32 v74, -v70, v73, v72
	v_fmac_f32_e32 v73, v74, v71
	v_fma_f32 v70, -v70, v73, v72
	v_mfma_f32_16x16x32_bf16 v[54:57], v[2:5], v[106:109], v[54:57]
	v_div_fmas_f32 v70, v70, v71, v73
	v_div_fixup_f32 v0, v70, v62, v0
	v_mul_f32_e32 v0, v58, v0
	v_cvt_pk_bf16_f32 v0, v0, s0
	ds_write_b16 v144, v0
	s_nop 2
	v_mul_f32_e32 v0, v54, v66
	v_mul_f32_e32 v54, 0xbfb8aa3b, v0
	v_exp_f32_e32 v54, v54
	v_mfma_f32_16x16x32_bf16 v[50:53], v[2:5], v[110:113], v[50:53]
	v_add_f32_e32 v54, 1.0, v54
	v_div_scale_f32 v58, s[12:13], v54, v54, v0
	v_rcp_f32_e32 v62, v58
	s_nop 4
	v_mul_f32_e32 v50, v50, v66
	v_mfma_f32_16x16x32_bf16 v[26:29], v[86:89], v[94:97], v[30:33]
	v_fma_f32 v66, -v58, v62, 1.0
	v_fmac_f32_e32 v62, v66, v62
	v_div_scale_f32 v66, vcc, v0, v54, v0
	v_mul_f32_e32 v70, v66, v62
	v_fma_f32 v71, -v58, v70, v66
	v_fmac_f32_e32 v70, v71, v62
	v_fma_f32 v58, -v58, v70, v66
	v_div_fmas_f32 v58, v58, v62, v70
	v_div_fixup_f32 v0, v58, v54, v0
	v_mul_f32_e32 v0, v50, v0
	v_cvt_pk_bf16_f32 v0, v0, s0
	ds_write_b16 v144, v0 offset:32
	v_mul_f32_e32 v0, v63, v67
	v_mul_f32_e32 v54, 0xbfb8aa3b, v0
	v_exp_f32_e32 v54, v54
	v_mul_f32_e32 v50, v59, v67
	v_mfma_f32_16x16x32_bf16 v[30:33], v[86:89], v[102:105], v[98:101]
	v_add_f32_e32 v54, 1.0, v54
	v_div_scale_f32 v58, s[12:13], v54, v54, v0
	v_rcp_f32_e32 v59, v58
	v_mfma_f32_16x16x32_bf16 v[10:13], v[90:93], v[94:97], v[14:17]
	v_fma_f32 v62, -v58, v59, 1.0
	v_fmac_f32_e32 v59, v62, v59
	v_div_scale_f32 v62, vcc, v0, v54, v0
	v_mul_f32_e32 v63, v62, v59
	v_fma_f32 v66, -v58, v63, v62
	v_fmac_f32_e32 v63, v66, v59
	v_fma_f32 v58, -v58, v63, v62
	v_div_fmas_f32 v58, v58, v59, v63
	v_div_fixup_f32 v0, v58, v54, v0
	v_mul_f32_e32 v0, v50, v0
	v_cvt_pk_bf16_f32 v0, v0, s0
	ds_write_b16 v145, v0
	v_mul_f32_e32 v0, v55, v67
	v_mul_f32_e32 v50, v51, v67
	v_mul_f32_e32 v51, 0xbfb8aa3b, v0
	v_exp_f32_e32 v51, v51
	v_mfma_f32_16x16x32_bf16 v[14:17], v[90:93], v[102:105], v[82:85]
	v_add_f32_e32 v51, 1.0, v51
	v_div_scale_f32 v54, s[12:13], v51, v51, v0
	v_rcp_f32_e32 v55, v54
	v_mfma_f32_16x16x32_bf16 v[2:5], v[90:93], v[106:109], v[6:9]
	v_fma_f32 v58, -v54, v55, 1.0
	v_fmac_f32_e32 v55, v58, v55
	v_div_scale_f32 v58, vcc, v0, v51, v0
	v_mul_f32_e32 v59, v58, v55
	v_fma_f32 v62, -v54, v59, v58
	v_fmac_f32_e32 v59, v62, v55
	v_fma_f32 v54, -v54, v59, v58
	v_div_fmas_f32 v54, v54, v55, v59
	v_div_fixup_f32 v0, v54, v51, v0
	v_mul_f32_e32 v0, v50, v0
	v_cvt_pk_bf16_f32 v0, v0, s0
	ds_write_b16 v145, v0 offset:32
	v_mul_f32_e32 v0, v64, v68
	v_mul_f32_e32 v51, 0xbfb8aa3b, v0
	v_exp_f32_e32 v51, v51
	v_mul_f32_e32 v50, v60, v68
	v_mfma_f32_16x16x32_bf16 v[6:9], v[90:93], v[110:113], v[78:81]
	v_add_f32_e32 v51, 1.0, v51
	v_div_scale_f32 v54, s[12:13], v51, v51, v0
	v_rcp_f32_e32 v55, v54
	s_nop 0
	v_fma_f32 v58, -v54, v55, 1.0
	v_fmac_f32_e32 v55, v58, v55
	v_div_scale_f32 v58, vcc, v0, v51, v0
	v_mul_f32_e32 v59, v58, v55
	v_fma_f32 v60, -v54, v59, v58
	v_fmac_f32_e32 v59, v60, v55
	v_fma_f32 v54, -v54, v59, v58
	v_div_fmas_f32 v54, v54, v55, v59
	v_div_fixup_f32 v0, v54, v51, v0
	v_mul_f32_e32 v0, v50, v0
	v_cvt_pk_bf16_f32 v0, v0, s0
	ds_write_b16 v146, v0
	v_mul_f32_e32 v0, v56, v68
	v_mul_f32_e32 v51, 0xbfb8aa3b, v0
	v_exp_f32_e32 v51, v51
	v_mul_f32_e32 v50, v52, v68
	v_add_f32_e32 v51, 1.0, v51
	v_min_f32_e32 v51, 0x7f7fffff, v51
	v_rcp_f32_e32 v230, v51
	s_nop 0
	v_fma_f32 v231, -v51, v230, 1.0
	v_fma_f32 v230, v231, v230, v230
	v_mul_f32_e32 v0, v0, v230
	v_mul_f32_e32 v0, v50, v0
	v_cvt_pk_bf16_f32 v0, v0, s0
	ds_write_b16 v146, v0 offset:32
	v_mul_f32_e32 v0, v65, v69
	v_mul_f32_e32 v51, 0xbfb8aa3b, v0
	v_exp_f32_e32 v51, v51
	v_mul_f32_e32 v50, v61, v69
	v_add_f32_e32 v51, 1.0, v51
	v_min_f32_e32 v51, 0x7f7fffff, v51
	v_rcp_f32_e32 v230, v51
	s_nop 0
	v_fma_f32 v231, -v51, v230, 1.0
	v_fma_f32 v230, v231, v230, v230
	v_mul_f32_e32 v0, v0, v230
	v_mul_f32_e32 v0, v50, v0
	v_cvt_pk_bf16_f32 v0, v0, s0
	ds_write_b16 v147, v0
	v_mul_f32_e32 v0, v57, v69
	v_mul_f32_e32 v51, 0xbfb8aa3b, v0
	v_exp_f32_e32 v51, v51
	v_mul_f32_e32 v50, v53, v69
	v_add_f32_e32 v51, 1.0, v51
	v_min_f32_e32 v51, 0x7f7fffff, v51
	v_rcp_f32_e32 v230, v51
	s_nop 0
	v_fma_f32 v231, -v51, v230, 1.0
	v_fma_f32 v230, v231, v230, v230
	v_mul_f32_e32 v0, v0, v230
	v_mul_f32_e32 v0, v50, v0
	ds_read_b128 v[50:53], v148
	v_cvt_pk_bf16_f32 v0, v0, s0
	ds_write_b16 v147, v0 offset:32
	s_waitcnt lgkmcnt(1)
; DI float siluf_(float x) { return x / (1.f + __expf(-x)); }
; template <int BN_OUT> DI void ct_put(bf16* lds, int row, int col, float v) { lds[row * (BN_OUT + 8) + col] = f2bf(v); }
; DI void phase_tail(const Ctx& c) {
;     ...
; #pragma unroll
;       for (int i = 0; i < 4; ++i)
; #pragma unroll
;         for (int r = 0; r < 4; ++r) {
;           const int row = wm * 64 + i * 16 + (lane >> 4) * 4 + r;
;           const float rs = rstd2[row];
; #pragma unroll
;           for (int pp = 0; pp < 2; ++pp) {
;             const float g = acc[i][2 * pp][r] * rs, u = acc[i][2 * pp + 1][r] * rs;
;             ct_put<128>(lds, row, (wn * 2 + pp) * 16 + (lane & 15), siluf_(g) * u);
;           }
;         }
	v_mul_f32_e32 v0, v42, v50
	v_mul_f32_e32 v42, v46, v50
	v_mul_f32_e32 v46, 0xbfb8aa3b, v0
	v_exp_f32_e32 v46, v46
	s_nop 0
	v_add_f32_e32 v46, 1.0, v46
	v_min_f32_e32 v46, 0x7f7fffff, v46
	v_rcp_f32_e32 v230, v46
	s_nop 0
	v_fma_f32 v231, -v46, v230, 1.0
	v_fma_f32 v230, v231, v230, v230
	v_mul_f32_e32 v0, v0, v230
	v_mul_f32_e32 v0, v42, v0
	v_cvt_pk_bf16_f32 v0, v0, s0
	ds_write_b16 v149, v0
	v_mul_f32_e32 v0, v34, v50
	v_mul_f32_e32 v34, v38, v50
	v_mul_f32_e32 v38, 0xbfb8aa3b, v0
	v_exp_f32_e32 v38, v38
	s_nop 0
	v_add_f32_e32 v38, 1.0, v38
	v_min_f32_e32 v38, 0x7f7fffff, v38
	v_rcp_f32_e32 v230, v38
	s_nop 0
	v_fma_f32 v231, -v38, v230, 1.0
	v_fma_f32 v230, v231, v230, v230
	v_mul_f32_e32 v0, v0, v230
	v_mul_f32_e32 v0, v34, v0
	v_cvt_pk_bf16_f32 v0, v0, s0
	ds_write_b16 v149, v0 offset:32
	v_mul_f32_e32 v0, v43, v51
	v_mul_f32_e32 v38, 0xbfb8aa3b, v0
	v_exp_f32_e32 v38, v38
	v_mul_f32_e32 v34, v47, v51
	v_add_f32_e32 v38, 1.0, v38
	v_min_f32_e32 v38, 0x7f7fffff, v38
	v_rcp_f32_e32 v230, v38
	s_nop 0
	v_fma_f32 v231, -v38, v230, 1.0
	v_fma_f32 v230, v231, v230, v230
	v_mul_f32_e32 v0, v0, v230
	v_mul_f32_e32 v0, v34, v0
	v_cvt_pk_bf16_f32 v0, v0, s0
	ds_write_b16 v150, v0
	v_mul_f32_e32 v0, v35, v51
	v_mul_f32_e32 v35, 0xbfb8aa3b, v0
	v_exp_f32_e32 v35, v35
	v_mul_f32_e32 v34, v39, v51
	v_add_f32_e32 v35, 1.0, v35
	v_min_f32_e32 v35, 0x7f7fffff, v35
	v_rcp_f32_e32 v230, v35
	s_nop 0
	v_fma_f32 v231, -v35, v230, 1.0
	v_fma_f32 v230, v231, v230, v230
	v_mul_f32_e32 v0, v0, v230
	v_mul_f32_e32 v0, v34, v0
	v_cvt_pk_bf16_f32 v0, v0, s0
	ds_write_b16 v150, v0 offset:32
	v_mul_f32_e32 v0, v44, v52
	v_mul_f32_e32 v35, 0xbfb8aa3b, v0
	v_exp_f32_e32 v35, v35
	v_mul_f32_e32 v34, v48, v52
	v_add_f32_e32 v35, 1.0, v35
	v_min_f32_e32 v35, 0x7f7fffff, v35
	v_rcp_f32_e32 v230, v35
	s_nop 0
	v_fma_f32 v231, -v35, v230, 1.0
	v_fma_f32 v230, v231, v230, v230
	v_mul_f32_e32 v0, v0, v230
	v_mul_f32_e32 v0, v34, v0
	v_cvt_pk_bf16_f32 v0, v0, s0
	ds_write_b16 v151, v0
	v_mul_f32_e32 v0, v36, v52
	v_mul_f32_e32 v35, 0xbfb8aa3b, v0
	v_exp_f32_e32 v35, v35
	v_mul_f32_e32 v34, v40, v52
	v_add_f32_e32 v35, 1.0, v35
	v_min_f32_e32 v35, 0x7f7fffff, v35
	v_rcp_f32_e32 v230, v35
	s_nop 0
	v_fma_f32 v231, -v35, v230, 1.0
	v_fma_f32 v230, v231, v230, v230
	v_mul_f32_e32 v0, v0, v230
	v_mul_f32_e32 v0, v34, v0
	v_cvt_pk_bf16_f32 v0, v0, s0
	ds_write_b16 v151, v0 offset:32
	v_mul_f32_e32 v0, v45, v53
	v_mul_f32_e32 v35, 0xbfb8aa3b, v0
	v_exp_f32_e32 v35, v35
	v_mul_f32_e32 v34, v49, v53
	v_add_f32_e32 v35, 1.0, v35
	v_min_f32_e32 v35, 0x7f7fffff, v35
	v_rcp_f32_e32 v230, v35
	s_nop 0
	v_fma_f32 v231, -v35, v230, 1.0
	v_fma_f32 v230, v231, v230, v230
	v_mul_f32_e32 v0, v0, v230
	v_mul_f32_e32 v0, v34, v0
	v_cvt_pk_bf16_f32 v0, v0, s0
	ds_write_b16 v152, v0
	v_mul_f32_e32 v0, v37, v53
	v_mul_f32_e32 v35, 0xbfb8aa3b, v0
	v_exp_f32_e32 v35, v35
	v_mul_f32_e32 v34, v41, v53
	v_add_f32_e32 v35, 1.0, v35
	v_min_f32_e32 v35, 0x7f7fffff, v35
	v_rcp_f32_e32 v230, v35
	s_nop 0
	v_fma_f32 v231, -v35, v230, 1.0
	v_fma_f32 v230, v231, v230, v230
	v_mul_f32_e32 v0, v0, v230
	v_mul_f32_e32 v0, v34, v0
	ds_read_b128 v[34:37], v153
	v_cvt_pk_bf16_f32 v0, v0, s0
	ds_write_b16 v152, v0 offset:32
	s_waitcnt lgkmcnt(1)
	v_mul_f32_e32 v0, v26, v34
	v_mul_f32_e32 v26, v30, v34
	v_mul_f32_e32 v30, 0xbfb8aa3b, v0
	v_exp_f32_e32 v30, v30
	s_nop 0
	v_add_f32_e32 v30, 1.0, v30
	v_min_f32_e32 v30, 0x7f7fffff, v30
	v_rcp_f32_e32 v230, v30
	s_nop 0
	v_fma_f32 v231, -v30, v230, 1.0
	v_fma_f32 v230, v231, v230, v230
	v_mul_f32_e32 v0, v0, v230
	v_mul_f32_e32 v0, v26, v0
	v_cvt_pk_bf16_f32 v0, v0, s0
	ds_write_b16 v154, v0
	v_mul_f32_e32 v0, v18, v34
	v_mul_f32_e32 v18, v22, v34
	v_mul_f32_e32 v22, 0xbfb8aa3b, v0
	v_exp_f32_e32 v22, v22
	s_nop 0
	v_add_f32_e32 v22, 1.0, v22
	v_min_f32_e32 v22, 0x7f7fffff, v22
	v_rcp_f32_e32 v230, v22
	s_nop 0
	v_fma_f32 v231, -v22, v230, 1.0
	v_fma_f32 v230, v231, v230, v230
	v_mul_f32_e32 v0, v0, v230
	v_mul_f32_e32 v0, v18, v0
	v_cvt_pk_bf16_f32 v0, v0, s0
	ds_write_b16 v154, v0 offset:32
	v_mul_f32_e32 v0, v27, v35
	v_mul_f32_e32 v22, 0xbfb8aa3b, v0
	v_exp_f32_e32 v22, v22
	v_mul_f32_e32 v18, v31, v35
	v_add_f32_e32 v22, 1.0, v22
	v_min_f32_e32 v22, 0x7f7fffff, v22
	v_rcp_f32_e32 v230, v22
	s_nop 0
	v_fma_f32 v231, -v22, v230, 1.0
	v_fma_f32 v230, v231, v230, v230
	v_mul_f32_e32 v0, v0, v230
	v_mul_f32_e32 v0, v18, v0
	v_cvt_pk_bf16_f32 v0, v0, s0
	ds_write_b16 v155, v0
	v_mul_f32_e32 v0, v19, v35
	v_mul_f32_e32 v19, 0xbfb8aa3b, v0
	v_exp_f32_e32 v19, v19
	v_mul_f32_e32 v18, v23, v35
	v_add_f32_e32 v19, 1.0, v19
	v_min_f32_e32 v19, 0x7f7fffff, v19
	v_rcp_f32_e32 v230, v19
	s_nop 0
	v_fma_f32 v231, -v19, v230, 1.0
	v_fma_f32 v230, v231, v230, v230
	v_mul_f32_e32 v0, v0, v230
	v_mul_f32_e32 v0, v18, v0
	v_cvt_pk_bf16_f32 v0, v0, s0
	ds_write_b16 v155, v0 offset:32
	v_mul_f32_e32 v0, v28, v36
	v_mul_f32_e32 v19, 0xbfb8aa3b, v0
	v_exp_f32_e32 v19, v19
	v_mul_f32_e32 v18, v32, v36
	v_add_f32_e32 v19, 1.0, v19
	v_min_f32_e32 v19, 0x7f7fffff, v19
	v_rcp_f32_e32 v230, v19
	s_nop 0
	v_fma_f32 v231, -v19, v230, 1.0
	v_fma_f32 v230, v231, v230, v230
	v_mul_f32_e32 v0, v0, v230
	v_mul_f32_e32 v0, v18, v0
	v_cvt_pk_bf16_f32 v0, v0, s0
	ds_write_b16 v156, v0
	v_mul_f32_e32 v0, v20, v36
	v_mul_f32_e32 v19, 0xbfb8aa3b, v0
	v_exp_f32_e32 v19, v19
	v_mul_f32_e32 v18, v24, v36
	v_add_f32_e32 v19, 1.0, v19
	v_min_f32_e32 v19, 0x7f7fffff, v19
	v_rcp_f32_e32 v230, v19
	s_nop 0
	v_fma_f32 v231, -v19, v230, 1.0
	v_fma_f32 v230, v231, v230, v230
	v_mul_f32_e32 v0, v0, v230
	v_mul_f32_e32 v0, v18, v0
	v_cvt_pk_bf16_f32 v0, v0, s0
	ds_write_b16 v156, v0 offset:32
	v_mul_f32_e32 v0, v29, v37
	v_mul_f32_e32 v19, 0xbfb8aa3b, v0
	v_exp_f32_e32 v19, v19
	v_mul_f32_e32 v18, v33, v37
	v_add_f32_e32 v19, 1.0, v19
	v_min_f32_e32 v19, 0x7f7fffff, v19
	v_rcp_f32_e32 v230, v19
	s_nop 0
	v_fma_f32 v231, -v19, v230, 1.0
	v_fma_f32 v230, v231, v230, v230
	v_mul_f32_e32 v0, v0, v230
	v_mul_f32_e32 v0, v18, v0
	v_cvt_pk_bf16_f32 v0, v0, s0
	ds_write_b16 v157, v0
	v_mul_f32_e32 v0, v21, v37
	v_mul_f32_e32 v19, 0xbfb8aa3b, v0
	v_exp_f32_e32 v19, v19
	v_mul_f32_e32 v18, v25, v37
	v_add_f32_e32 v19, 1.0, v19
	v_min_f32_e32 v19, 0x7f7fffff, v19
	v_rcp_f32_e32 v230, v19
	s_nop 0
	v_fma_f32 v231, -v19, v230, 1.0
	v_fma_f32 v230, v231, v230, v230
	v_mul_f32_e32 v0, v0, v230
	v_mul_f32_e32 v0, v18, v0
	ds_read_b128 v[18:21], v158
	v_cvt_pk_bf16_f32 v0, v0, s0
	ds_write_b16 v157, v0 offset:32
	s_waitcnt lgkmcnt(1)
; DI float siluf_(float x) { return x / (1.f + __expf(-x)); }
; template <int BN_OUT> DI void ct_put(bf16* lds, int row, int col, float v) { lds[row * (BN_OUT + 8) + col] = f2bf(v); }
; DI void phase_tail(const Ctx& c) {
;     ...
; #pragma unroll
;       for (int i = 0; i < 4; ++i)
; #pragma unroll
;         for (int r = 0; r < 4; ++r) {
;           const int row = wm * 64 + i * 16 + (lane >> 4) * 4 + r;
;           const float rs = rstd2[row];
; #pragma unroll
;           for (int pp = 0; pp < 2; ++pp) {
;             const float g = acc[i][2 * pp][r] * rs, u = acc[i][2 * pp + 1][r] * rs;
;             ct_put<128>(lds, row, (wn * 2 + pp) * 16 + (lane & 15), siluf_(g) * u);
;           }
;         }
;       ct_flush<128, 128>(lds, F + (size_t)m0 * DFF + nt * 128, DFF);
	v_mul_f32_e32 v0, v10, v18
	v_mul_f32_e32 v10, v14, v18
	v_mul_f32_e32 v14, 0xbfb8aa3b, v0
	v_exp_f32_e32 v14, v14
	s_nop 0
	v_add_f32_e32 v14, 1.0, v14
	v_min_f32_e32 v14, 0x7f7fffff, v14
	v_rcp_f32_e32 v230, v14
	s_nop 0
	v_fma_f32 v231, -v14, v230, 1.0
	v_fma_f32 v230, v231, v230, v230
	v_mul_f32_e32 v0, v0, v230
	v_mul_f32_e32 v0, v10, v0
	v_cvt_pk_bf16_f32 v0, v0, s0
	ds_write_b16 v159, v0
	v_mul_f32_e32 v0, v2, v18
	v_mul_f32_e32 v2, v6, v18
	v_mul_f32_e32 v6, 0xbfb8aa3b, v0
	v_exp_f32_e32 v6, v6
	s_nop 0
	v_add_f32_e32 v6, 1.0, v6
	v_min_f32_e32 v6, 0x7f7fffff, v6
	v_rcp_f32_e32 v230, v6
	s_nop 0
	v_fma_f32 v231, -v6, v230, 1.0
	v_fma_f32 v230, v231, v230, v230
	v_mul_f32_e32 v0, v0, v230
	v_mul_f32_e32 v0, v2, v0
	v_cvt_pk_bf16_f32 v0, v0, s0
	ds_write_b16 v159, v0 offset:32
	v_mul_f32_e32 v0, v11, v19
	v_mul_f32_e32 v6, 0xbfb8aa3b, v0
	v_exp_f32_e32 v6, v6
	v_mul_f32_e32 v2, v15, v19
	v_add_f32_e32 v6, 1.0, v6
	v_min_f32_e32 v6, 0x7f7fffff, v6
	v_rcp_f32_e32 v230, v6
	s_nop 0
	v_fma_f32 v231, -v6, v230, 1.0
	v_fma_f32 v230, v231, v230, v230
	v_mul_f32_e32 v0, v0, v230
	v_mul_f32_e32 v0, v2, v0
	v_cvt_pk_bf16_f32 v0, v0, s0
	ds_write_b16 v160, v0
	v_mul_f32_e32 v0, v3, v19
	v_mul_f32_e32 v3, 0xbfb8aa3b, v0
	v_exp_f32_e32 v3, v3
	v_mul_f32_e32 v2, v7, v19
	v_add_f32_e32 v3, 1.0, v3
	v_min_f32_e32 v3, 0x7f7fffff, v3
	v_rcp_f32_e32 v230, v3
	s_nop 0
	v_fma_f32 v231, -v3, v230, 1.0
	v_fma_f32 v230, v231, v230, v230
	v_mul_f32_e32 v0, v0, v230
	v_mul_f32_e32 v0, v2, v0
	v_cvt_pk_bf16_f32 v0, v0, s0
	ds_write_b16 v160, v0 offset:32
	v_mul_f32_e32 v0, v12, v20
	v_mul_f32_e32 v3, 0xbfb8aa3b, v0
	v_exp_f32_e32 v3, v3
	v_mul_f32_e32 v2, v16, v20
	v_add_f32_e32 v3, 1.0, v3
	v_min_f32_e32 v3, 0x7f7fffff, v3
	v_rcp_f32_e32 v230, v3
	s_nop 0
	v_fma_f32 v231, -v3, v230, 1.0
	v_fma_f32 v230, v231, v230, v230
	v_mul_f32_e32 v0, v0, v230
	v_mul_f32_e32 v0, v2, v0
	v_cvt_pk_bf16_f32 v0, v0, s0
	ds_write_b16 v161, v0
	v_mul_f32_e32 v0, v4, v20
	v_mul_f32_e32 v3, 0xbfb8aa3b, v0
	v_exp_f32_e32 v3, v3
	v_mul_f32_e32 v2, v8, v20
	v_add_f32_e32 v3, 1.0, v3
	v_min_f32_e32 v3, 0x7f7fffff, v3
	v_rcp_f32_e32 v230, v3
	s_nop 0
	v_fma_f32 v231, -v3, v230, 1.0
	v_fma_f32 v230, v231, v230, v230
	v_mul_f32_e32 v0, v0, v230
	v_mul_f32_e32 v0, v2, v0
	v_cvt_pk_bf16_f32 v0, v0, s0
	ds_write_b16 v161, v0 offset:32
	v_mul_f32_e32 v0, v13, v21
	v_mul_f32_e32 v3, 0xbfb8aa3b, v0
	v_exp_f32_e32 v3, v3
	v_mul_f32_e32 v2, v17, v21
	v_add_f32_e32 v3, 1.0, v3
	v_min_f32_e32 v3, 0x7f7fffff, v3
	v_rcp_f32_e32 v230, v3
	s_nop 0
	v_fma_f32 v231, -v3, v230, 1.0
	v_fma_f32 v230, v231, v230, v230
	v_mul_f32_e32 v0, v0, v230
	v_mul_f32_e32 v0, v2, v0
	v_cvt_pk_bf16_f32 v0, v0, s0
	ds_write_b16 v162, v0
	v_mul_f32_e32 v0, v5, v21
	v_mul_f32_e32 v3, 0xbfb8aa3b, v0
	v_exp_f32_e32 v3, v3
	v_mul_f32_e32 v2, v9, v21
	v_add_f32_e32 v3, 1.0, v3
	v_min_f32_e32 v3, 0x7f7fffff, v3
	v_rcp_f32_e32 v230, v3
	s_nop 0
	v_fma_f32 v231, -v3, v230, 1.0
	v_fma_f32 v230, v231, v230, v230
	v_mul_f32_e32 v0, v0, v230
	v_mul_f32_e32 v0, v2, v0
	v_cvt_pk_bf16_f32 v0, v0, s0
	ds_write_b16 v162, v0 offset:32
	v_mov_b32_e32 v0, v186
	s_waitcnt lgkmcnt(0)
	s_barrier
	s_nop 0
	v_cmp_gt_i32_e32 vcc, s11, v0
	s_and_saveexec_b64 s[28:29], vcc
	s_movk_i32 s14, 0x5ff
	s_movk_i32 s15, 0x1600
	s_cbranch_execz .LBB0_853
	s_lshl_b32 s11, s10, 8
	s_add_u32 s30, s24, s11
	s_addc_u32 s31, s25, 0
	v_lshl_add_u32 v2, v0, 4, v190
	v_lshlrev_b32_e32 v3, 3, v0
	s_mov_b64 s[34:35], 0
